# setprio moved outside barriers, redundant lgkmcnt wait removed, pre-MFMA barrier skewed down by 4 MFMAs in all GEMM mainloops
# speedup vs baseline: 1.0064x; 1.0064x over previous
; #define PG8_STAGE(bufoff, gbase, voff) do { _Pragma("unroll") for (int _i = 0; _i < 2; ++_i) \
;         __builtin_amdgcn_global_load_lds((const unsigned*)((const char*)(gbase) + (voff)[_i]), (PG8_LAS unsigned*)(lds + (bufoff) + ldsw + _i * 8192), 16, 0, 0); } while (0)
; #define PG8_LDA(dst, b, h) do { _Pragma("unroll") for (int m = 0; m < 4; ++m) _Pragma("unroll") for (int k = 0; k < 2; ++k) dst[m][k] = *(const PG8_LAS bf16x8*)(lds + PG8_SA(b, h) + aoff + m * 2048 + k * 1024); } while (0)
; #define PG8_LDB(dst, b, h) do { _Pragma("unroll") for (int n = 0; n < 2; ++n) _Pragma("unroll") for (int k = 0; k < 2; ++k) dst[n][k] = *(const PG8_LAS bf16x8*)(lds + PG8_SB(b, h) + boff + n * 2048 + k * 1024); } while (0)
; #define PG8_MMA(ai, bj, At, Bt) do { __builtin_amdgcn_s_setprio(1); _Pragma("unroll") for (int m = 0; m < 4; ++m) _Pragma("unroll") for (int n = 0; n < 2; ++n) _Pragma("unroll") for (int k = 0; k < 2; ++k) \
;         acc[ai][bj][m][n] = __builtin_amdgcn_mfma_f32_16x16x32_bf16(Bt[n][k], At[m][k], acc[ai][bj][m][n], 0, 0, 0); __builtin_amdgcn_s_setprio(0); } while (0)
; #define PG8_WAIT_V(n) asm volatile("s_waitcnt vmcnt(" #n ")" ::: "memory")
; #define PG8_BAR __builtin_amdgcn_s_barrier()
; template <class Epi, class Sched, bool ALIGN_EPI = false, bool SP2 = false>
; __device__ __forceinline__ void gemm_phase(PG8_LAS unsigned char* lds, const Gemm g, const Sched& S, const Epi& E) {
;     ...
;         for (int t = 0; t < nt; t += 2) {
;             const bool last = (t == nt - 2);
;             const char* a1 = cA + (size_t)(t + 1) * kstep;
;             const char* a2 = last ? nA : cA + (size_t)(t + 2) * kstep; const char* b2 = last ? nB : cB + (size_t)(t + 2) * kstep;
;             const char* a3 = a2 + kstep; const char* b3 = b2 + kstep;
;             if (last && has_next) S.a_ready(nxt);
;             if constexpr (SP2) {
;             PG8_LDB(B0, 0, 0); PG8_LDB(B1, 0, 1); PG8_SCHED; PG8_LDA(At, 0, 0); PG8_STAGE(PG8_SA(1, 1), a1 + hstepA, voffA);
;             PG8_WAIT_V(8); PG8_WAIT_L(0); PG8_BAR; PG8_MMA(0, 0, At, B0); PG8_MMA(0, 1, At, B1); PG8_BAR; PG8_SCHED;
;             PG8_LDA(At, 0, 1); PG8_STAGE(PG8_SB(0, 0), b2, voffB); PG8_STAGE(PG8_SB(0, 1), b2 + hstepB, voffB); PG8_STAGE(PG8_SA(0, 0), a2, voffA);
;             PG8_WAIT_V(8); PG8_WAIT_L(0); PG8_BAR; PG8_MMA(1, 0, At, B0); PG8_MMA(1, 1, At, B1); PG8_BAR; PG8_SCHED;
.LBB0_96:
	ds_read_b128 v[112:115], v168
	ds_read_b128 v[116:119], v168 offset:1024
	ds_read_b128 v[172:175], v168 offset:2048
	ds_read_b128 v[176:179], v168 offset:3072
	ds_read_b128 v[182:185], v169
	ds_read_b128 v[186:189], v169 offset:1024
	ds_read_b128 v[190:193], v169 offset:2048
	ds_read_b128 v[194:197], v169 offset:3072
	s_add_u32 s26, s24, 0xfff80080
	s_addc_u32 s27, s25, -1
	s_cmp_eq_u32 s97, 28
	s_cselect_b32 s29, s13, s27
	s_cselect_b32 s28, s23, s26
	s_cselect_b32 s27, s15, s96
	s_cselect_b32 s26, s91, s95
	v_lshl_add_u64 v[164:165], s[24:25], 0, v[154:155]
	s_add_i32 m0, s34, 0xc000
	ds_read_b128 v[202:205], v170
	ds_read_b128 v[206:209], v170 offset:1024
	ds_read_b128 v[210:213], v170 offset:2048
	ds_read_b128 v[214:217], v170 offset:3072
	ds_read_b128 v[218:221], v170 offset:4096
	ds_read_b128 v[222:225], v170 offset:5120
	ds_read_b128 v[226:229], v170 offset:6144
	ds_read_b128 v[230:233], v170 offset:7168
	global_load_lds_dwordx4 v[164:165], off
	v_lshl_add_u64 v[164:165], s[24:25], 0, v[156:157]
	s_add_i32 m0, s34, 0xe000
	s_nop 0
	global_load_lds_dwordx4 v[164:165], off
	s_waitcnt vmcnt(8)
	s_waitcnt lgkmcnt(0)
	s_setprio 1
	v_mfma_f32_16x16x32_bf16 v[132:135], v[112:115], v[202:205], v[132:135]
	v_mfma_f32_16x16x32_bf16 v[128:131], v[172:175], v[202:205], v[128:131]
	v_mfma_f32_16x16x32_bf16 v[108:111], v[112:115], v[210:213], v[108:111]
	v_mfma_f32_16x16x32_bf16 v[104:107], v[172:175], v[210:213], v[104:107]
	s_barrier
	v_mfma_f32_16x16x32_bf16 v[92:95], v[112:115], v[218:221], v[92:95]
	v_mfma_f32_16x16x32_bf16 v[88:91], v[172:175], v[218:221], v[88:91]
	v_mfma_f32_16x16x32_bf16 v[76:79], v[112:115], v[226:229], v[76:79]
	v_mfma_f32_16x16x32_bf16 v[72:75], v[172:175], v[226:229], v[72:75]
	v_mfma_f32_16x16x32_bf16 v[132:135], v[116:119], v[206:209], v[132:135]
	v_mfma_f32_16x16x32_bf16 v[128:131], v[176:179], v[206:209], v[128:131]
	v_mfma_f32_16x16x32_bf16 v[108:111], v[116:119], v[214:217], v[108:111]
	v_mfma_f32_16x16x32_bf16 v[104:107], v[176:179], v[214:217], v[104:107]
	v_mfma_f32_16x16x32_bf16 v[92:95], v[116:119], v[222:225], v[92:95]
	v_mfma_f32_16x16x32_bf16 v[88:91], v[176:179], v[222:225], v[88:91]
	v_mfma_f32_16x16x32_bf16 v[76:79], v[116:119], v[230:233], v[76:79]
	v_mfma_f32_16x16x32_bf16 v[72:75], v[176:179], v[230:233], v[72:75]
	v_mfma_f32_16x16x32_bf16 v[124:127], v[182:185], v[202:205], v[124:127]
	v_mfma_f32_16x16x32_bf16 v[120:123], v[190:193], v[202:205], v[120:123]
	v_mfma_f32_16x16x32_bf16 v[100:103], v[182:185], v[210:213], v[100:103]
	v_mfma_f32_16x16x32_bf16 v[96:99], v[190:193], v[210:213], v[96:99]
	v_mfma_f32_16x16x32_bf16 v[84:87], v[182:185], v[218:221], v[84:87]
	v_mfma_f32_16x16x32_bf16 v[80:83], v[190:193], v[218:221], v[80:83]
	v_mfma_f32_16x16x32_bf16 v[68:71], v[182:185], v[226:229], v[68:71]
	v_mfma_f32_16x16x32_bf16 v[64:67], v[190:193], v[226:229], v[64:67]
	v_mfma_f32_16x16x32_bf16 v[124:127], v[186:189], v[206:209], v[124:127]
	v_mfma_f32_16x16x32_bf16 v[120:123], v[194:197], v[206:209], v[120:123]
	v_mfma_f32_16x16x32_bf16 v[100:103], v[186:189], v[214:217], v[100:103]
	v_mfma_f32_16x16x32_bf16 v[96:99], v[194:197], v[214:217], v[96:99]
	v_mfma_f32_16x16x32_bf16 v[84:87], v[186:189], v[222:225], v[84:87]
	v_mfma_f32_16x16x32_bf16 v[80:83], v[194:197], v[222:225], v[80:83]
	v_mfma_f32_16x16x32_bf16 v[68:71], v[186:189], v[230:233], v[68:71]
	v_mfma_f32_16x16x32_bf16 v[64:67], v[194:197], v[230:233], v[64:67]
	s_barrier
	s_setprio 0
	s_add_i32 s44, s82, s19
	v_lshl_add_u64 v[164:165], s[26:27], 0, v[146:147]
	s_mov_b32 m0, s44
	ds_read_b128 v[202:205], v170 offset:16384
	ds_read_b128 v[206:209], v170 offset:17408
	ds_read_b128 v[210:213], v170 offset:18432
	ds_read_b128 v[214:217], v170 offset:19456
	ds_read_b128 v[218:221], v170 offset:20480
	ds_read_b128 v[222:225], v170 offset:21504
	ds_read_b128 v[226:229], v170 offset:22528
	ds_read_b128 v[230:233], v170 offset:23552
	global_load_lds_dwordx4 v[164:165], off
	s_add_i32 m0, s44, 0x2000
	s_add_u32 vcc_lo, s26, 0x80000
	v_lshl_add_u64 v[198:199], s[26:27], 0, v[142:143]
	s_addc_u32 vcc_hi, s27, 0
	s_add_i32 s44, s83, s19
	global_load_lds_dwordx4 v[198:199], off
	v_lshl_add_u64 v[234:235], vcc, 0, v[146:147]
	s_mov_b32 m0, s44
	v_lshl_add_u64 v[236:237], s[28:29], 0, v[144:145]
	global_load_lds_dwordx4 v[234:235], off
	v_lshl_add_u64 v[234:235], vcc, 0, v[142:143]
	s_add_i32 m0, s44, 0x2000
	s_nop 0
	global_load_lds_dwordx4 v[234:235], off
	v_lshl_add_u64 v[234:235], s[28:29], 0, v[148:149]
	s_mov_b32 m0, s34
	s_nop 0
	global_load_lds_dwordx4 v[234:235], off
	s_mov_b32 m0, s35
	s_nop 0
	global_load_lds_dwordx4 v[236:237], off
	s_waitcnt vmcnt(8)
	s_waitcnt lgkmcnt(0)
	s_setprio 1
	v_mfma_f32_16x16x32_bf16 v[60:63], v[112:115], v[202:205], v[60:63]
	v_mfma_f32_16x16x32_bf16 v[56:59], v[172:175], v[202:205], v[56:59]
	v_mfma_f32_16x16x32_bf16 v[44:47], v[112:115], v[210:213], v[44:47]
	v_mfma_f32_16x16x32_bf16 v[40:43], v[172:175], v[210:213], v[40:43]
	s_barrier
; #define PG8_STAGE(bufoff, gbase, voff) do { _Pragma("unroll") for (int _i = 0; _i < 2; ++_i) \
;         __builtin_amdgcn_global_load_lds((const unsigned*)((const char*)(gbase) + (voff)[_i]), (PG8_LAS unsigned*)(lds + (bufoff) + ldsw + _i * 8192), 16, 0, 0); } while (0)
; #define PG8_LDA(dst, b, h) do { _Pragma("unroll") for (int m = 0; m < 4; ++m) _Pragma("unroll") for (int k = 0; k < 2; ++k) dst[m][k] = *(const PG8_LAS bf16x8*)(lds + PG8_SA(b, h) + aoff + m * 2048 + k * 1024); } while (0)
; #define PG8_LDB(dst, b, h) do { _Pragma("unroll") for (int n = 0; n < 2; ++n) _Pragma("unroll") for (int k = 0; k < 2; ++k) dst[n][k] = *(const PG8_LAS bf16x8*)(lds + PG8_SB(b, h) + boff + n * 2048 + k * 1024); } while (0)
; #define PG8_MMA(ai, bj, At, Bt) do { __builtin_amdgcn_s_setprio(1); _Pragma("unroll") for (int m = 0; m < 4; ++m) _Pragma("unroll") for (int n = 0; n < 2; ++n) _Pragma("unroll") for (int k = 0; k < 2; ++k) \
;         acc[ai][bj][m][n] = __builtin_amdgcn_mfma_f32_16x16x32_bf16(Bt[n][k], At[m][k], acc[ai][bj][m][n], 0, 0, 0); __builtin_amdgcn_s_setprio(0); } while (0)
; #define PG8_WAIT_V(n) asm volatile("s_waitcnt vmcnt(" #n ")" ::: "memory")
; #define PG8_WAIT_L(n) asm volatile("s_waitcnt lgkmcnt(" #n ")" ::: "memory")
; #define PG8_BAR __builtin_amdgcn_s_barrier()
; #define PG8_SCHED __builtin_amdgcn_sched_barrier(0)
; template <class Epi, class Sched, bool ALIGN_EPI = false, bool SP2 = false>
; __device__ __forceinline__ void gemm_phase(PG8_LAS unsigned char* lds, const Gemm g, const Sched& S, const Epi& E) {
;     ...
;             PG8_WAIT_V(8); PG8_WAIT_L(0); PG8_BAR; PG8_MMA(1, 0, At, B0); PG8_MMA(1, 1, At, B1); PG8_BAR; PG8_SCHED;
;             PG8_LDB(B0, 1, 0); PG8_LDB(B1, 1, 1); PG8_SCHED; PG8_LDA(At, 1, 0); PG8_STAGE(PG8_SA(0, 1), a2 + hstepA, voffA);
;             PG8_WAIT_V(8); PG8_WAIT_L(0); PG8_BAR; PG8_MMA(0, 0, At, B0); PG8_MMA(0, 1, At, B1); PG8_BAR; PG8_SCHED;
	v_mfma_f32_16x16x32_bf16 v[28:31], v[112:115], v[218:221], v[28:31]
	v_mfma_f32_16x16x32_bf16 v[24:27], v[172:175], v[218:221], v[24:27]
	v_mfma_f32_16x16x32_bf16 v[12:15], v[112:115], v[226:229], v[12:15]
	v_mfma_f32_16x16x32_bf16 v[8:11], v[172:175], v[226:229], v[8:11]
	v_mfma_f32_16x16x32_bf16 v[60:63], v[116:119], v[206:209], v[60:63]
	v_mfma_f32_16x16x32_bf16 v[56:59], v[176:179], v[206:209], v[56:59]
	v_mfma_f32_16x16x32_bf16 v[44:47], v[116:119], v[214:217], v[44:47]
	v_mfma_f32_16x16x32_bf16 v[40:43], v[176:179], v[214:217], v[40:43]
	v_mfma_f32_16x16x32_bf16 v[28:31], v[116:119], v[222:225], v[28:31]
	v_mfma_f32_16x16x32_bf16 v[24:27], v[176:179], v[222:225], v[24:27]
	v_mfma_f32_16x16x32_bf16 v[12:15], v[116:119], v[230:233], v[12:15]
	v_mfma_f32_16x16x32_bf16 v[8:11], v[176:179], v[230:233], v[8:11]
	v_mfma_f32_16x16x32_bf16 v[52:55], v[182:185], v[202:205], v[52:55]
	v_mfma_f32_16x16x32_bf16 v[48:51], v[190:193], v[202:205], v[48:51]
	v_mfma_f32_16x16x32_bf16 v[36:39], v[182:185], v[210:213], v[36:39]
	v_mfma_f32_16x16x32_bf16 v[32:35], v[190:193], v[210:213], v[32:35]
	v_mfma_f32_16x16x32_bf16 v[20:23], v[182:185], v[218:221], v[20:23]
	v_mfma_f32_16x16x32_bf16 v[16:19], v[190:193], v[218:221], v[16:19]
	v_mfma_f32_16x16x32_bf16 v[4:7], v[182:185], v[226:229], v[4:7]
	v_mfma_f32_16x16x32_bf16 v[0:3], v[190:193], v[226:229], v[0:3]
	v_mfma_f32_16x16x32_bf16 v[52:55], v[186:189], v[206:209], v[52:55]
	v_mfma_f32_16x16x32_bf16 v[48:51], v[194:197], v[206:209], v[48:51]
	v_mfma_f32_16x16x32_bf16 v[36:39], v[186:189], v[214:217], v[36:39]
	v_mfma_f32_16x16x32_bf16 v[32:35], v[194:197], v[214:217], v[32:35]
	v_mfma_f32_16x16x32_bf16 v[20:23], v[186:189], v[222:225], v[20:23]
	v_mfma_f32_16x16x32_bf16 v[16:19], v[194:197], v[222:225], v[16:19]
	v_mfma_f32_16x16x32_bf16 v[4:7], v[186:189], v[230:233], v[4:7]
	v_mfma_f32_16x16x32_bf16 v[0:3], v[194:197], v[230:233], v[0:3]
	s_barrier
	s_setprio 0
	s_add_i32 s44, 0, 0x18000
	v_add_u32_e32 v162, s44, v166
	s_add_i32 s45, 0, 0x1c000
	ds_read_b128 v[112:115], v162
	ds_read_b128 v[116:119], v162 offset:1024
	ds_read_b128 v[172:175], v162 offset:2048
	ds_read_b128 v[176:179], v162 offset:3072
	v_add_u32_e32 v162, s45, v166
	ds_read_b128 v[182:185], v162
	ds_read_b128 v[186:189], v162 offset:1024
	ds_read_b128 v[190:193], v162 offset:2048
	ds_read_b128 v[194:197], v162 offset:3072
	s_add_u32 s28, s28, 0x80000
	s_addc_u32 s29, s29, 0
	s_mov_b32 m0, s36
	v_lshl_add_u64 v[238:239], s[28:29], 0, v[148:149]
	ds_read_b128 v[202:205], v170 offset:32768
	ds_read_b128 v[206:209], v170 offset:33792
	ds_read_b128 v[210:213], v170 offset:34816
	ds_read_b128 v[214:217], v170 offset:35840
	ds_read_b128 v[218:221], v170 offset:36864
	ds_read_b128 v[222:225], v170 offset:37888
	ds_read_b128 v[226:229], v170 offset:38912
	ds_read_b128 v[230:233], v170 offset:39936
	global_load_lds_dwordx4 v[238:239], off
	v_lshl_add_u64 v[238:239], s[28:29], 0, v[144:145]
	s_mov_b32 m0, s37
	s_nop 0
	global_load_lds_dwordx4 v[238:239], off
	s_waitcnt vmcnt(8)
	s_waitcnt lgkmcnt(0)
	s_setprio 1
	v_mfma_f32_16x16x32_bf16 v[132:135], v[112:115], v[202:205], v[132:135]
	v_mfma_f32_16x16x32_bf16 v[128:131], v[172:175], v[202:205], v[128:131]
	v_mfma_f32_16x16x32_bf16 v[108:111], v[112:115], v[210:213], v[108:111]
	v_mfma_f32_16x16x32_bf16 v[104:107], v[172:175], v[210:213], v[104:107]
	s_barrier
	v_mfma_f32_16x16x32_bf16 v[92:95], v[112:115], v[218:221], v[92:95]
	v_mfma_f32_16x16x32_bf16 v[88:91], v[172:175], v[218:221], v[88:91]
	v_mfma_f32_16x16x32_bf16 v[76:79], v[112:115], v[226:229], v[76:79]
	v_mfma_f32_16x16x32_bf16 v[72:75], v[172:175], v[226:229], v[72:75]
	v_mfma_f32_16x16x32_bf16 v[132:135], v[116:119], v[206:209], v[132:135]
	v_mfma_f32_16x16x32_bf16 v[128:131], v[176:179], v[206:209], v[128:131]
	v_mfma_f32_16x16x32_bf16 v[108:111], v[116:119], v[214:217], v[108:111]
	v_mfma_f32_16x16x32_bf16 v[104:107], v[176:179], v[214:217], v[104:107]
	v_mfma_f32_16x16x32_bf16 v[92:95], v[116:119], v[222:225], v[92:95]
	v_mfma_f32_16x16x32_bf16 v[88:91], v[176:179], v[222:225], v[88:91]
	v_mfma_f32_16x16x32_bf16 v[76:79], v[116:119], v[230:233], v[76:79]
	v_mfma_f32_16x16x32_bf16 v[72:75], v[176:179], v[230:233], v[72:75]
	v_mfma_f32_16x16x32_bf16 v[124:127], v[182:185], v[202:205], v[124:127]
	v_mfma_f32_16x16x32_bf16 v[120:123], v[190:193], v[202:205], v[120:123]
	v_mfma_f32_16x16x32_bf16 v[100:103], v[182:185], v[210:213], v[100:103]
	v_mfma_f32_16x16x32_bf16 v[96:99], v[190:193], v[210:213], v[96:99]
	v_mfma_f32_16x16x32_bf16 v[84:87], v[182:185], v[218:221], v[84:87]
	v_mfma_f32_16x16x32_bf16 v[80:83], v[190:193], v[218:221], v[80:83]
	v_mfma_f32_16x16x32_bf16 v[68:71], v[182:185], v[226:229], v[68:71]
	v_mfma_f32_16x16x32_bf16 v[64:67], v[190:193], v[226:229], v[64:67]
	v_mfma_f32_16x16x32_bf16 v[124:127], v[186:189], v[206:209], v[124:127]
	v_mfma_f32_16x16x32_bf16 v[120:123], v[194:197], v[206:209], v[120:123]
	v_mfma_f32_16x16x32_bf16 v[100:103], v[186:189], v[214:217], v[100:103]
	v_mfma_f32_16x16x32_bf16 v[96:99], v[194:197], v[214:217], v[96:99]
	v_mfma_f32_16x16x32_bf16 v[84:87], v[186:189], v[222:225], v[84:87]
	v_mfma_f32_16x16x32_bf16 v[80:83], v[194:197], v[222:225], v[80:83]
	v_mfma_f32_16x16x32_bf16 v[68:71], v[186:189], v[230:233], v[68:71]
	v_mfma_f32_16x16x32_bf16 v[64:67], v[194:197], v[230:233], v[64:67]
	s_barrier
; #define PG8_STAGE(bufoff, gbase, voff) do { _Pragma("unroll") for (int _i = 0; _i < 2; ++_i) \
;         __builtin_amdgcn_global_load_lds((const unsigned*)((const char*)(gbase) + (voff)[_i]), (PG8_LAS unsigned*)(lds + (bufoff) + ldsw + _i * 8192), 16, 0, 0); } while (0)
; #define PG8_LDA(dst, b, h) do { _Pragma("unroll") for (int m = 0; m < 4; ++m) _Pragma("unroll") for (int k = 0; k < 2; ++k) dst[m][k] = *(const PG8_LAS bf16x8*)(lds + PG8_SA(b, h) + aoff + m * 2048 + k * 1024); } while (0)
; #define PG8_MMA(ai, bj, At, Bt) do { __builtin_amdgcn_s_setprio(1); _Pragma("unroll") for (int m = 0; m < 4; ++m) _Pragma("unroll") for (int n = 0; n < 2; ++n) _Pragma("unroll") for (int k = 0; k < 2; ++k) \
;         acc[ai][bj][m][n] = __builtin_amdgcn_mfma_f32_16x16x32_bf16(Bt[n][k], At[m][k], acc[ai][bj][m][n], 0, 0, 0); __builtin_amdgcn_s_setprio(0); } while (0)
; #define PG8_WAIT_V(n) asm volatile("s_waitcnt vmcnt(" #n ")" ::: "memory")
; #define PG8_WAIT_L(n) asm volatile("s_waitcnt lgkmcnt(" #n ")" ::: "memory")
; #define PG8_BAR __builtin_amdgcn_s_barrier()
; #define PG8_SCHED __builtin_amdgcn_sched_barrier(0)
; template <class Epi, class Sched, bool ALIGN_EPI = false, bool SP2 = false>
; __device__ __forceinline__ void gemm_phase(PG8_LAS unsigned char* lds, const Gemm g, const Sched& S, const Epi& E) {
;     ...
;             PG8_WAIT_V(8); PG8_WAIT_L(0); PG8_BAR; PG8_MMA(0, 0, At, B0); PG8_MMA(0, 1, At, B1); PG8_BAR; PG8_SCHED;
;             PG8_LDA(At, 1, 1); PG8_STAGE(PG8_SB(1, 0), b3, voffB); PG8_STAGE(PG8_SB(1, 1), b3 + hstepB, voffB); PG8_STAGE(PG8_SA(1, 0), a3, voffA);
;             PG8_WAIT_V(8); PG8_WAIT_L(0); PG8_BAR; PG8_MMA(1, 0, At, B0); PG8_MMA(1, 1, At, B1); PG8_BAR; PG8_SCHED;
;     ...
;         if constexpr (ALIGN_EPI) { if (wr == 0) PG8_BAR; }
	s_setprio 0
	s_add_i32 s28, s44, s19
	v_lshl_add_u64 v[164:165], v[164:165], 0, s[8:9]
	s_mov_b32 m0, s28
	ds_read_b128 v[202:205], v170 offset:49152
	ds_read_b128 v[206:209], v170 offset:50176
	ds_read_b128 v[210:213], v170 offset:51200
	ds_read_b128 v[214:217], v170 offset:52224
	ds_read_b128 v[218:221], v170 offset:53248
	ds_read_b128 v[222:225], v170 offset:54272
	ds_read_b128 v[226:229], v170 offset:55296
	ds_read_b128 v[230:233], v170 offset:56320
	global_load_lds_dwordx4 v[164:165], off
	s_add_i32 m0, s28, 0x2000
	s_add_u32 s26, s26, 0x80080
	v_lshl_add_u64 v[164:165], v[198:199], 0, s[8:9]
	s_addc_u32 s27, s27, 0
	s_add_i32 s28, s45, s19
	global_load_lds_dwordx4 v[164:165], off
	v_lshl_add_u64 v[164:165], s[26:27], 0, v[146:147]
	s_mov_b32 m0, s28
	s_nop 0
	global_load_lds_dwordx4 v[164:165], off
	v_lshl_add_u64 v[164:165], s[26:27], 0, v[142:143]
	s_add_i32 m0, s28, 0x2000
	s_nop 0
	global_load_lds_dwordx4 v[164:165], off
	v_lshl_add_u64 v[164:165], v[234:235], 0, s[8:9]
	s_mov_b32 m0, s39
	s_nop 0
	global_load_lds_dwordx4 v[164:165], off
	v_lshl_add_u64 v[164:165], v[236:237], 0, s[8:9]
	s_mov_b32 m0, s78
	s_nop 0
	global_load_lds_dwordx4 v[164:165], off
	s_waitcnt vmcnt(8)
	s_waitcnt lgkmcnt(0)
	s_setprio 1
	v_mfma_f32_16x16x32_bf16 v[60:63], v[112:115], v[202:205], v[60:63]
	v_mfma_f32_16x16x32_bf16 v[56:59], v[172:175], v[202:205], v[56:59]
	v_mfma_f32_16x16x32_bf16 v[44:47], v[112:115], v[210:213], v[44:47]
	v_mfma_f32_16x16x32_bf16 v[40:43], v[172:175], v[210:213], v[40:43]
	s_barrier
	v_mfma_f32_16x16x32_bf16 v[28:31], v[112:115], v[218:221], v[28:31]
	v_mfma_f32_16x16x32_bf16 v[24:27], v[172:175], v[218:221], v[24:27]
	v_mfma_f32_16x16x32_bf16 v[12:15], v[112:115], v[226:229], v[12:15]
	v_mfma_f32_16x16x32_bf16 v[8:11], v[172:175], v[226:229], v[8:11]
	v_mfma_f32_16x16x32_bf16 v[60:63], v[116:119], v[206:209], v[60:63]
	v_mfma_f32_16x16x32_bf16 v[56:59], v[176:179], v[206:209], v[56:59]
	v_mfma_f32_16x16x32_bf16 v[44:47], v[116:119], v[214:217], v[44:47]
	v_mfma_f32_16x16x32_bf16 v[40:43], v[176:179], v[214:217], v[40:43]
	v_mfma_f32_16x16x32_bf16 v[28:31], v[116:119], v[222:225], v[28:31]
	v_mfma_f32_16x16x32_bf16 v[24:27], v[176:179], v[222:225], v[24:27]
	v_mfma_f32_16x16x32_bf16 v[12:15], v[116:119], v[230:233], v[12:15]
	v_mfma_f32_16x16x32_bf16 v[8:11], v[176:179], v[230:233], v[8:11]
	v_mfma_f32_16x16x32_bf16 v[52:55], v[182:185], v[202:205], v[52:55]
	v_mfma_f32_16x16x32_bf16 v[48:51], v[190:193], v[202:205], v[48:51]
	v_mfma_f32_16x16x32_bf16 v[36:39], v[182:185], v[210:213], v[36:39]
	v_mfma_f32_16x16x32_bf16 v[32:35], v[190:193], v[210:213], v[32:35]
	v_mfma_f32_16x16x32_bf16 v[20:23], v[182:185], v[218:221], v[20:23]
	v_mfma_f32_16x16x32_bf16 v[16:19], v[190:193], v[218:221], v[16:19]
	v_mfma_f32_16x16x32_bf16 v[4:7], v[182:185], v[226:229], v[4:7]
	v_mfma_f32_16x16x32_bf16 v[0:3], v[190:193], v[226:229], v[0:3]
	v_mfma_f32_16x16x32_bf16 v[52:55], v[186:189], v[206:209], v[52:55]
	v_mfma_f32_16x16x32_bf16 v[48:51], v[194:197], v[206:209], v[48:51]
	v_mfma_f32_16x16x32_bf16 v[36:39], v[186:189], v[214:217], v[36:39]
	v_mfma_f32_16x16x32_bf16 v[32:35], v[194:197], v[214:217], v[32:35]
	v_mfma_f32_16x16x32_bf16 v[20:23], v[186:189], v[222:225], v[20:23]
	v_mfma_f32_16x16x32_bf16 v[16:19], v[194:197], v[222:225], v[16:19]
	v_mfma_f32_16x16x32_bf16 v[4:7], v[186:189], v[230:233], v[4:7]
	v_mfma_f32_16x16x32_bf16 v[0:3], v[194:197], v[230:233], v[0:3]
	s_barrier
	s_setprio 0
	s_add_i32 s97, s97, 2
	s_add_u32 s24, s24, 0x100
	s_addc_u32 s25, s25, 0
	s_add_u32 s95, s95, 0x100
	s_addc_u32 s96, s96, 0
	s_cmp_gt_u32 s97, 29
	s_cbranch_scc0 .LBB0_96
	s_and_b64 vcc, exec, s[10:11]
	s_cbranch_vccz .LBB0_99
	s_barrier

; #define PG8_STAGE(bufoff, gbase, voff) do { _Pragma("unroll") for (int _i = 0; _i < 2; ++_i) \
;         __builtin_amdgcn_global_load_lds((const unsigned*)((const char*)(gbase) + (voff)[_i]), (PG8_LAS unsigned*)(lds + (bufoff) + ldsw + _i * 8192), 16, 0, 0); } while (0)
; #define PG8_LDA(dst, b, h) do { _Pragma("unroll") for (int m = 0; m < 4; ++m) _Pragma("unroll") for (int k = 0; k < 2; ++k) dst[m][k] = *(const PG8_LAS bf16x8*)(lds + PG8_SA(b, h) + aoff + m * 2048 + k * 1024); } while (0)
; #define PG8_LDB(dst, b, h) do { _Pragma("unroll") for (int n = 0; n < 2; ++n) _Pragma("unroll") for (int k = 0; k < 2; ++k) dst[n][k] = *(const PG8_LAS bf16x8*)(lds + PG8_SB(b, h) + boff + n * 2048 + k * 1024); } while (0)
; #define PG8_MMA(ai, bj, At, Bt) do { __builtin_amdgcn_s_setprio(1); _Pragma("unroll") for (int m = 0; m < 4; ++m) _Pragma("unroll") for (int n = 0; n < 2; ++n) _Pragma("unroll") for (int k = 0; k < 2; ++k) \
;         acc[ai][bj][m][n] = __builtin_amdgcn_mfma_f32_16x16x32_bf16(Bt[n][k], At[m][k], acc[ai][bj][m][n], 0, 0, 0); __builtin_amdgcn_s_setprio(0); } while (0)
; #define PG8_WAIT_V(n) asm volatile("s_waitcnt vmcnt(" #n ")" ::: "memory")
; #define PG8_BAR __builtin_amdgcn_s_barrier()
; template <class Epi, class Sched, bool ALIGN_EPI = false, bool SP2 = false>
; __device__ __forceinline__ void gemm_phase(PG8_LAS unsigned char* lds, const Gemm g, const Sched& S, const Epi& E) {
;     ...
;         for (int t = 0; t < nt; t += 2) {
;             const bool last = (t == nt - 2);
;             const char* a1 = cA + (size_t)(t + 1) * kstep;
;             const char* a2 = last ? nA : cA + (size_t)(t + 2) * kstep; const char* b2 = last ? nB : cB + (size_t)(t + 2) * kstep;
;             const char* a3 = a2 + kstep; const char* b3 = b2 + kstep;
;             if (last && has_next) S.a_ready(nxt);
;             if constexpr (SP2) {
;             PG8_LDB(B0, 0, 0); PG8_LDB(B1, 0, 1); PG8_SCHED; PG8_LDA(At, 0, 0); PG8_STAGE(PG8_SA(1, 1), a1 + hstepA, voffA);
;             PG8_WAIT_V(8); PG8_WAIT_L(0); PG8_BAR; PG8_MMA(0, 0, At, B0); PG8_MMA(0, 1, At, B1); PG8_BAR; PG8_SCHED;
;             PG8_LDA(At, 0, 1); PG8_STAGE(PG8_SB(0, 0), b2, voffB); PG8_STAGE(PG8_SB(0, 1), b2 + hstepB, voffB); PG8_STAGE(PG8_SA(0, 0), a2, voffA);
;             PG8_WAIT_V(8); PG8_WAIT_L(0); PG8_BAR; PG8_MMA(1, 0, At, B0); PG8_MMA(1, 1, At, B1); PG8_BAR; PG8_SCHED;
.LBB0_315:
	ds_read_b128 v[162:165], v158
	ds_read_b128 v[166:169], v158 offset:1024
	ds_read_b128 v[170:173], v158 offset:2048
	ds_read_b128 v[174:177], v158 offset:3072
	ds_read_b128 v[182:185], v159
	ds_read_b128 v[186:189], v159 offset:1024
	ds_read_b128 v[190:193], v159 offset:2048
	ds_read_b128 v[194:197], v159 offset:3072
	s_add_u32 s30, s28, 0xfff80080
	s_addc_u32 s31, s29, -1
	s_cmp_eq_u32 vcc_hi, 28
	s_cselect_b32 s35, s21, s31
	s_cselect_b32 s34, s95, s30
	s_cselect_b32 s31, s23, vcc_lo
	s_cselect_b32 s30, s96, s97
	v_lshl_add_u64 v[178:179], s[28:29], 0, v[140:141]
	s_add_i32 m0, s19, 0xc000
	ds_read_b128 v[202:205], v160
	ds_read_b128 v[206:209], v160 offset:1024
	ds_read_b128 v[210:213], v160 offset:2048
	ds_read_b128 v[214:217], v160 offset:3072
	ds_read_b128 v[218:221], v160 offset:4096
	ds_read_b128 v[222:225], v160 offset:5120
	ds_read_b128 v[226:229], v160 offset:6144
	ds_read_b128 v[230:233], v160 offset:7168
	global_load_lds_dwordx4 v[178:179], off
	v_lshl_add_u64 v[178:179], s[28:29], 0, v[142:143]
	s_add_i32 m0, s19, 0xe000
	s_nop 0
	global_load_lds_dwordx4 v[178:179], off
	s_waitcnt vmcnt(8)
	s_waitcnt lgkmcnt(0)
	s_setprio 1
	v_mfma_f32_16x16x32_bf16 v[124:127], v[162:165], v[202:205], v[124:127]
	v_mfma_f32_16x16x32_bf16 v[120:123], v[170:173], v[202:205], v[120:123]
	v_mfma_f32_16x16x32_bf16 v[116:119], v[162:165], v[210:213], v[116:119]
	v_mfma_f32_16x16x32_bf16 v[112:115], v[170:173], v[210:213], v[112:115]
	s_barrier
	v_mfma_f32_16x16x32_bf16 v[100:103], v[162:165], v[218:221], v[100:103]
	v_mfma_f32_16x16x32_bf16 v[96:99], v[170:173], v[218:221], v[96:99]
	v_mfma_f32_16x16x32_bf16 v[84:87], v[162:165], v[226:229], v[84:87]
	v_mfma_f32_16x16x32_bf16 v[80:83], v[170:173], v[226:229], v[80:83]
	v_mfma_f32_16x16x32_bf16 v[124:127], v[166:169], v[206:209], v[124:127]
	v_mfma_f32_16x16x32_bf16 v[120:123], v[174:177], v[206:209], v[120:123]
	v_mfma_f32_16x16x32_bf16 v[116:119], v[166:169], v[214:217], v[116:119]
	v_mfma_f32_16x16x32_bf16 v[112:115], v[174:177], v[214:217], v[112:115]
	v_mfma_f32_16x16x32_bf16 v[100:103], v[166:169], v[222:225], v[100:103]
	v_mfma_f32_16x16x32_bf16 v[96:99], v[174:177], v[222:225], v[96:99]
	v_mfma_f32_16x16x32_bf16 v[84:87], v[166:169], v[230:233], v[84:87]
	v_mfma_f32_16x16x32_bf16 v[80:83], v[174:177], v[230:233], v[80:83]
	v_mfma_f32_16x16x32_bf16 v[108:111], v[182:185], v[202:205], v[108:111]
	v_mfma_f32_16x16x32_bf16 v[104:107], v[190:193], v[202:205], v[104:107]
	v_mfma_f32_16x16x32_bf16 v[92:95], v[182:185], v[210:213], v[92:95]
	v_mfma_f32_16x16x32_bf16 v[88:91], v[190:193], v[210:213], v[88:91]
	v_mfma_f32_16x16x32_bf16 v[76:79], v[182:185], v[218:221], v[76:79]
	v_mfma_f32_16x16x32_bf16 v[72:75], v[190:193], v[218:221], v[72:75]
	v_mfma_f32_16x16x32_bf16 v[68:71], v[182:185], v[226:229], v[68:71]
	v_mfma_f32_16x16x32_bf16 v[64:67], v[190:193], v[226:229], v[64:67]
	v_mfma_f32_16x16x32_bf16 v[108:111], v[186:189], v[206:209], v[108:111]
	v_mfma_f32_16x16x32_bf16 v[104:107], v[194:197], v[206:209], v[104:107]
	v_mfma_f32_16x16x32_bf16 v[92:95], v[186:189], v[214:217], v[92:95]
	v_mfma_f32_16x16x32_bf16 v[88:91], v[194:197], v[214:217], v[88:91]
	v_mfma_f32_16x16x32_bf16 v[76:79], v[186:189], v[222:225], v[76:79]
	v_mfma_f32_16x16x32_bf16 v[72:75], v[194:197], v[222:225], v[72:75]
	v_mfma_f32_16x16x32_bf16 v[68:71], v[186:189], v[230:233], v[68:71]
	v_mfma_f32_16x16x32_bf16 v[64:67], v[194:197], v[230:233], v[64:67]
	s_barrier
	s_setprio 0
	s_add_i32 s44, s86, s39
	v_lshl_add_u64 v[178:179], s[30:31], 0, v[132:133]
	s_mov_b32 m0, s44
	ds_read_b128 v[202:205], v160 offset:16384
	ds_read_b128 v[206:209], v160 offset:17408
	ds_read_b128 v[210:213], v160 offset:18432
	ds_read_b128 v[214:217], v160 offset:19456
	ds_read_b128 v[218:221], v160 offset:20480
	ds_read_b128 v[222:225], v160 offset:21504
	ds_read_b128 v[226:229], v160 offset:22528
	ds_read_b128 v[230:233], v160 offset:23552
	global_load_lds_dwordx4 v[178:179], off
	s_add_i32 m0, s44, 0x2000
	s_add_u32 s44, s30, 0x80000
	v_lshl_add_u64 v[198:199], s[30:31], 0, v[138:139]
	s_addc_u32 s45, s31, 0
	s_add_i32 s3, s87, s39
	global_load_lds_dwordx4 v[198:199], off
	v_lshl_add_u64 v[234:235], s[44:45], 0, v[132:133]
	s_mov_b32 m0, s3
	v_lshl_add_u64 v[236:237], s[34:35], 0, v[134:135]
	global_load_lds_dwordx4 v[234:235], off
	v_lshl_add_u64 v[234:235], s[44:45], 0, v[138:139]
	s_add_i32 m0, s3, 0x2000
	s_nop 0
	global_load_lds_dwordx4 v[234:235], off
	v_lshl_add_u64 v[234:235], s[34:35], 0, v[130:131]
	s_mov_b32 m0, s19
	s_nop 0
	global_load_lds_dwordx4 v[234:235], off
	s_mov_b32 m0, s52
	s_nop 0
	global_load_lds_dwordx4 v[236:237], off
	s_waitcnt vmcnt(8)
	s_waitcnt lgkmcnt(0)
	s_setprio 1
	v_mfma_f32_16x16x32_bf16 v[60:63], v[162:165], v[202:205], v[60:63]
	v_mfma_f32_16x16x32_bf16 v[56:59], v[170:173], v[202:205], v[56:59]
	v_mfma_f32_16x16x32_bf16 v[52:55], v[162:165], v[210:213], v[52:55]
	v_mfma_f32_16x16x32_bf16 v[48:51], v[170:173], v[210:213], v[48:51]
	s_barrier
; #define PG8_STAGE(bufoff, gbase, voff) do { _Pragma("unroll") for (int _i = 0; _i < 2; ++_i) \
;         __builtin_amdgcn_global_load_lds((const unsigned*)((const char*)(gbase) + (voff)[_i]), (PG8_LAS unsigned*)(lds + (bufoff) + ldsw + _i * 8192), 16, 0, 0); } while (0)
; #define PG8_LDA(dst, b, h) do { _Pragma("unroll") for (int m = 0; m < 4; ++m) _Pragma("unroll") for (int k = 0; k < 2; ++k) dst[m][k] = *(const PG8_LAS bf16x8*)(lds + PG8_SA(b, h) + aoff + m * 2048 + k * 1024); } while (0)
; #define PG8_LDB(dst, b, h) do { _Pragma("unroll") for (int n = 0; n < 2; ++n) _Pragma("unroll") for (int k = 0; k < 2; ++k) dst[n][k] = *(const PG8_LAS bf16x8*)(lds + PG8_SB(b, h) + boff + n * 2048 + k * 1024); } while (0)
; #define PG8_MMA(ai, bj, At, Bt) do { __builtin_amdgcn_s_setprio(1); _Pragma("unroll") for (int m = 0; m < 4; ++m) _Pragma("unroll") for (int n = 0; n < 2; ++n) _Pragma("unroll") for (int k = 0; k < 2; ++k) \
;         acc[ai][bj][m][n] = __builtin_amdgcn_mfma_f32_16x16x32_bf16(Bt[n][k], At[m][k], acc[ai][bj][m][n], 0, 0, 0); __builtin_amdgcn_s_setprio(0); } while (0)
; #define PG8_WAIT_V(n) asm volatile("s_waitcnt vmcnt(" #n ")" ::: "memory")
; #define PG8_WAIT_L(n) asm volatile("s_waitcnt lgkmcnt(" #n ")" ::: "memory")
; #define PG8_BAR __builtin_amdgcn_s_barrier()
; #define PG8_SCHED __builtin_amdgcn_sched_barrier(0)
; template <class Epi, class Sched, bool ALIGN_EPI = false, bool SP2 = false>
; __device__ __forceinline__ void gemm_phase(PG8_LAS unsigned char* lds, const Gemm g, const Sched& S, const Epi& E) {
;     ...
;             PG8_WAIT_V(8); PG8_WAIT_L(0); PG8_BAR; PG8_MMA(1, 0, At, B0); PG8_MMA(1, 1, At, B1); PG8_BAR; PG8_SCHED;
;             PG8_LDB(B0, 1, 0); PG8_LDB(B1, 1, 1); PG8_SCHED; PG8_LDA(At, 1, 0); PG8_STAGE(PG8_SA(0, 1), a2 + hstepA, voffA);
;             PG8_WAIT_V(8); PG8_WAIT_L(0); PG8_BAR; PG8_MMA(0, 0, At, B0); PG8_MMA(0, 1, At, B1); PG8_BAR; PG8_SCHED;
	v_mfma_f32_16x16x32_bf16 v[36:39], v[162:165], v[218:221], v[36:39]
	v_mfma_f32_16x16x32_bf16 v[32:35], v[170:173], v[218:221], v[32:35]
	v_mfma_f32_16x16x32_bf16 v[20:23], v[162:165], v[226:229], v[20:23]
	v_mfma_f32_16x16x32_bf16 v[16:19], v[170:173], v[226:229], v[16:19]
	v_mfma_f32_16x16x32_bf16 v[60:63], v[166:169], v[206:209], v[60:63]
	v_mfma_f32_16x16x32_bf16 v[56:59], v[174:177], v[206:209], v[56:59]
	v_mfma_f32_16x16x32_bf16 v[52:55], v[166:169], v[214:217], v[52:55]
	v_mfma_f32_16x16x32_bf16 v[48:51], v[174:177], v[214:217], v[48:51]
	v_mfma_f32_16x16x32_bf16 v[36:39], v[166:169], v[222:225], v[36:39]
	v_mfma_f32_16x16x32_bf16 v[32:35], v[174:177], v[222:225], v[32:35]
	v_mfma_f32_16x16x32_bf16 v[20:23], v[166:169], v[230:233], v[20:23]
	v_mfma_f32_16x16x32_bf16 v[16:19], v[174:177], v[230:233], v[16:19]
	v_mfma_f32_16x16x32_bf16 v[44:47], v[182:185], v[202:205], v[44:47]
	v_mfma_f32_16x16x32_bf16 v[40:43], v[190:193], v[202:205], v[40:43]
	v_mfma_f32_16x16x32_bf16 v[28:31], v[182:185], v[210:213], v[28:31]
	v_mfma_f32_16x16x32_bf16 v[24:27], v[190:193], v[210:213], v[24:27]
	v_mfma_f32_16x16x32_bf16 v[12:15], v[182:185], v[218:221], v[12:15]
	v_mfma_f32_16x16x32_bf16 v[8:11], v[190:193], v[218:221], v[8:11]
	v_mfma_f32_16x16x32_bf16 v[4:7], v[182:185], v[226:229], v[4:7]
	v_mfma_f32_16x16x32_bf16 v[0:3], v[190:193], v[226:229], v[0:3]
	v_mfma_f32_16x16x32_bf16 v[44:47], v[186:189], v[206:209], v[44:47]
	v_mfma_f32_16x16x32_bf16 v[40:43], v[194:197], v[206:209], v[40:43]
	v_mfma_f32_16x16x32_bf16 v[28:31], v[186:189], v[214:217], v[28:31]
	v_mfma_f32_16x16x32_bf16 v[24:27], v[194:197], v[214:217], v[24:27]
	v_mfma_f32_16x16x32_bf16 v[12:15], v[186:189], v[222:225], v[12:15]
	v_mfma_f32_16x16x32_bf16 v[8:11], v[194:197], v[222:225], v[8:11]
	v_mfma_f32_16x16x32_bf16 v[4:7], v[186:189], v[230:233], v[4:7]
	v_mfma_f32_16x16x32_bf16 v[0:3], v[194:197], v[230:233], v[0:3]
	s_barrier
	s_setprio 0
	s_add_i32 s3, 0, 0x18000
	v_add_u32_e32 v161, s3, v156
	s_add_i32 s44, 0, 0x1c000
	ds_read_b128 v[162:165], v161
	ds_read_b128 v[166:169], v161 offset:1024
	ds_read_b128 v[170:173], v161 offset:2048
	ds_read_b128 v[174:177], v161 offset:3072
	v_add_u32_e32 v161, s44, v156
	ds_read_b128 v[182:185], v161
	ds_read_b128 v[186:189], v161 offset:1024
	ds_read_b128 v[190:193], v161 offset:2048
	ds_read_b128 v[194:197], v161 offset:3072
	s_add_u32 s34, s34, 0x80000
	s_addc_u32 s35, s35, 0
	s_mov_b32 m0, s53
	v_lshl_add_u64 v[238:239], s[34:35], 0, v[130:131]
	ds_read_b128 v[202:205], v160 offset:32768
	ds_read_b128 v[206:209], v160 offset:33792
	ds_read_b128 v[210:213], v160 offset:34816
	ds_read_b128 v[214:217], v160 offset:35840
	ds_read_b128 v[218:221], v160 offset:36864
	ds_read_b128 v[222:225], v160 offset:37888
	ds_read_b128 v[226:229], v160 offset:38912
	ds_read_b128 v[230:233], v160 offset:39936
	global_load_lds_dwordx4 v[238:239], off
	v_lshl_add_u64 v[238:239], s[34:35], 0, v[134:135]
	s_mov_b32 m0, s62
	s_nop 0
	global_load_lds_dwordx4 v[238:239], off
	s_waitcnt vmcnt(8)
	s_waitcnt lgkmcnt(0)
	s_setprio 1
	v_mfma_f32_16x16x32_bf16 v[124:127], v[162:165], v[202:205], v[124:127]
	v_mfma_f32_16x16x32_bf16 v[120:123], v[170:173], v[202:205], v[120:123]
	v_mfma_f32_16x16x32_bf16 v[116:119], v[162:165], v[210:213], v[116:119]
	v_mfma_f32_16x16x32_bf16 v[112:115], v[170:173], v[210:213], v[112:115]
	s_barrier
	v_mfma_f32_16x16x32_bf16 v[100:103], v[162:165], v[218:221], v[100:103]
	v_mfma_f32_16x16x32_bf16 v[96:99], v[170:173], v[218:221], v[96:99]
	v_mfma_f32_16x16x32_bf16 v[84:87], v[162:165], v[226:229], v[84:87]
	v_mfma_f32_16x16x32_bf16 v[80:83], v[170:173], v[226:229], v[80:83]
	v_mfma_f32_16x16x32_bf16 v[124:127], v[166:169], v[206:209], v[124:127]
	v_mfma_f32_16x16x32_bf16 v[120:123], v[174:177], v[206:209], v[120:123]
	v_mfma_f32_16x16x32_bf16 v[116:119], v[166:169], v[214:217], v[116:119]
	v_mfma_f32_16x16x32_bf16 v[112:115], v[174:177], v[214:217], v[112:115]
	v_mfma_f32_16x16x32_bf16 v[100:103], v[166:169], v[222:225], v[100:103]
	v_mfma_f32_16x16x32_bf16 v[96:99], v[174:177], v[222:225], v[96:99]
	v_mfma_f32_16x16x32_bf16 v[84:87], v[166:169], v[230:233], v[84:87]
	v_mfma_f32_16x16x32_bf16 v[80:83], v[174:177], v[230:233], v[80:83]
	v_mfma_f32_16x16x32_bf16 v[108:111], v[182:185], v[202:205], v[108:111]
	v_mfma_f32_16x16x32_bf16 v[104:107], v[190:193], v[202:205], v[104:107]
	v_mfma_f32_16x16x32_bf16 v[92:95], v[182:185], v[210:213], v[92:95]
	v_mfma_f32_16x16x32_bf16 v[88:91], v[190:193], v[210:213], v[88:91]
	v_mfma_f32_16x16x32_bf16 v[76:79], v[182:185], v[218:221], v[76:79]
	v_mfma_f32_16x16x32_bf16 v[72:75], v[190:193], v[218:221], v[72:75]
	v_mfma_f32_16x16x32_bf16 v[68:71], v[182:185], v[226:229], v[68:71]
	v_mfma_f32_16x16x32_bf16 v[64:67], v[190:193], v[226:229], v[64:67]
	v_mfma_f32_16x16x32_bf16 v[108:111], v[186:189], v[206:209], v[108:111]
	v_mfma_f32_16x16x32_bf16 v[104:107], v[194:197], v[206:209], v[104:107]
	v_mfma_f32_16x16x32_bf16 v[92:95], v[186:189], v[214:217], v[92:95]
	v_mfma_f32_16x16x32_bf16 v[88:91], v[194:197], v[214:217], v[88:91]
	v_mfma_f32_16x16x32_bf16 v[76:79], v[186:189], v[222:225], v[76:79]
	v_mfma_f32_16x16x32_bf16 v[72:75], v[194:197], v[222:225], v[72:75]
	v_mfma_f32_16x16x32_bf16 v[68:71], v[186:189], v[230:233], v[68:71]
	v_mfma_f32_16x16x32_bf16 v[64:67], v[194:197], v[230:233], v[64:67]
	s_barrier
; #define PG8_STAGE(bufoff, gbase, voff) do { _Pragma("unroll") for (int _i = 0; _i < 2; ++_i) \
;         __builtin_amdgcn_global_load_lds((const unsigned*)((const char*)(gbase) + (voff)[_i]), (PG8_LAS unsigned*)(lds + (bufoff) + ldsw + _i * 8192), 16, 0, 0); } while (0)
; #define PG8_LDA(dst, b, h) do { _Pragma("unroll") for (int m = 0; m < 4; ++m) _Pragma("unroll") for (int k = 0; k < 2; ++k) dst[m][k] = *(const PG8_LAS bf16x8*)(lds + PG8_SA(b, h) + aoff + m * 2048 + k * 1024); } while (0)
; #define PG8_MMA(ai, bj, At, Bt) do { __builtin_amdgcn_s_setprio(1); _Pragma("unroll") for (int m = 0; m < 4; ++m) _Pragma("unroll") for (int n = 0; n < 2; ++n) _Pragma("unroll") for (int k = 0; k < 2; ++k) \
;         acc[ai][bj][m][n] = __builtin_amdgcn_mfma_f32_16x16x32_bf16(Bt[n][k], At[m][k], acc[ai][bj][m][n], 0, 0, 0); __builtin_amdgcn_s_setprio(0); } while (0)
; #define PG8_WAIT_V(n) asm volatile("s_waitcnt vmcnt(" #n ")" ::: "memory")
; #define PG8_WAIT_L(n) asm volatile("s_waitcnt lgkmcnt(" #n ")" ::: "memory")
; #define PG8_BAR __builtin_amdgcn_s_barrier()
; #define PG8_SCHED __builtin_amdgcn_sched_barrier(0)
; template <class Epi, class Sched, bool ALIGN_EPI = false, bool SP2 = false>
; __device__ __forceinline__ void gemm_phase(PG8_LAS unsigned char* lds, const Gemm g, const Sched& S, const Epi& E) {
;     ...
;             PG8_WAIT_V(8); PG8_WAIT_L(0); PG8_BAR; PG8_MMA(0, 0, At, B0); PG8_MMA(0, 1, At, B1); PG8_BAR; PG8_SCHED;
;             PG8_LDA(At, 1, 1); PG8_STAGE(PG8_SB(1, 0), b3, voffB); PG8_STAGE(PG8_SB(1, 1), b3 + hstepB, voffB); PG8_STAGE(PG8_SA(1, 0), a3, voffA);
;             PG8_WAIT_V(8); PG8_WAIT_L(0); PG8_BAR; PG8_MMA(1, 0, At, B0); PG8_MMA(1, 1, At, B1); PG8_BAR; PG8_SCHED;
;     ...
;         if constexpr (ALIGN_EPI) { if (wr == 0) PG8_BAR; }
	s_setprio 0
	s_add_i32 s3, s3, s39
	v_lshl_add_u64 v[178:179], v[178:179], 0, s[8:9]
	s_mov_b32 m0, s3
	ds_read_b128 v[202:205], v160 offset:49152
	ds_read_b128 v[206:209], v160 offset:50176
	ds_read_b128 v[210:213], v160 offset:51200
	ds_read_b128 v[214:217], v160 offset:52224
	ds_read_b128 v[218:221], v160 offset:53248
	ds_read_b128 v[222:225], v160 offset:54272
	ds_read_b128 v[226:229], v160 offset:55296
	ds_read_b128 v[230:233], v160 offset:56320
	global_load_lds_dwordx4 v[178:179], off
	s_add_i32 m0, s3, 0x2000
	s_add_u32 s30, s30, 0x80080
	v_lshl_add_u64 v[178:179], v[198:199], 0, s[8:9]
	s_addc_u32 s31, s31, 0
	s_add_i32 s3, s44, s39
	global_load_lds_dwordx4 v[178:179], off
	v_lshl_add_u64 v[178:179], s[30:31], 0, v[132:133]
	s_mov_b32 m0, s3
	s_nop 0
	global_load_lds_dwordx4 v[178:179], off
	v_lshl_add_u64 v[178:179], s[30:31], 0, v[138:139]
	s_add_i32 m0, s3, 0x2000
	s_nop 0
	global_load_lds_dwordx4 v[178:179], off
	v_lshl_add_u64 v[178:179], v[234:235], 0, s[8:9]
	s_mov_b32 m0, s64
	s_nop 0
	global_load_lds_dwordx4 v[178:179], off
	v_lshl_add_u64 v[178:179], v[236:237], 0, s[8:9]
	s_mov_b32 m0, s65
	s_nop 0
	global_load_lds_dwordx4 v[178:179], off
	s_waitcnt vmcnt(8)
	s_waitcnt lgkmcnt(0)
	s_setprio 1
	v_mfma_f32_16x16x32_bf16 v[60:63], v[162:165], v[202:205], v[60:63]
	v_mfma_f32_16x16x32_bf16 v[56:59], v[170:173], v[202:205], v[56:59]
	v_mfma_f32_16x16x32_bf16 v[52:55], v[162:165], v[210:213], v[52:55]
	v_mfma_f32_16x16x32_bf16 v[48:51], v[170:173], v[210:213], v[48:51]
	s_barrier
	v_mfma_f32_16x16x32_bf16 v[36:39], v[162:165], v[218:221], v[36:39]
	v_mfma_f32_16x16x32_bf16 v[32:35], v[170:173], v[218:221], v[32:35]
	v_mfma_f32_16x16x32_bf16 v[20:23], v[162:165], v[226:229], v[20:23]
	v_mfma_f32_16x16x32_bf16 v[16:19], v[170:173], v[226:229], v[16:19]
	v_mfma_f32_16x16x32_bf16 v[60:63], v[166:169], v[206:209], v[60:63]
	v_mfma_f32_16x16x32_bf16 v[56:59], v[174:177], v[206:209], v[56:59]
	v_mfma_f32_16x16x32_bf16 v[52:55], v[166:169], v[214:217], v[52:55]
	v_mfma_f32_16x16x32_bf16 v[48:51], v[174:177], v[214:217], v[48:51]
	v_mfma_f32_16x16x32_bf16 v[36:39], v[166:169], v[222:225], v[36:39]
	v_mfma_f32_16x16x32_bf16 v[32:35], v[174:177], v[222:225], v[32:35]
	v_mfma_f32_16x16x32_bf16 v[20:23], v[166:169], v[230:233], v[20:23]
	v_mfma_f32_16x16x32_bf16 v[16:19], v[174:177], v[230:233], v[16:19]
	v_mfma_f32_16x16x32_bf16 v[44:47], v[182:185], v[202:205], v[44:47]
	v_mfma_f32_16x16x32_bf16 v[40:43], v[190:193], v[202:205], v[40:43]
	v_mfma_f32_16x16x32_bf16 v[28:31], v[182:185], v[210:213], v[28:31]
	v_mfma_f32_16x16x32_bf16 v[24:27], v[190:193], v[210:213], v[24:27]
	v_mfma_f32_16x16x32_bf16 v[12:15], v[182:185], v[218:221], v[12:15]
	v_mfma_f32_16x16x32_bf16 v[8:11], v[190:193], v[218:221], v[8:11]
	v_mfma_f32_16x16x32_bf16 v[4:7], v[182:185], v[226:229], v[4:7]
	v_mfma_f32_16x16x32_bf16 v[0:3], v[190:193], v[226:229], v[0:3]
	v_mfma_f32_16x16x32_bf16 v[44:47], v[186:189], v[206:209], v[44:47]
	v_mfma_f32_16x16x32_bf16 v[40:43], v[194:197], v[206:209], v[40:43]
	v_mfma_f32_16x16x32_bf16 v[28:31], v[186:189], v[214:217], v[28:31]
	v_mfma_f32_16x16x32_bf16 v[24:27], v[194:197], v[214:217], v[24:27]
	v_mfma_f32_16x16x32_bf16 v[12:15], v[186:189], v[222:225], v[12:15]
	v_mfma_f32_16x16x32_bf16 v[8:11], v[194:197], v[222:225], v[8:11]
	v_mfma_f32_16x16x32_bf16 v[4:7], v[186:189], v[230:233], v[4:7]
	v_mfma_f32_16x16x32_bf16 v[0:3], v[194:197], v[230:233], v[0:3]
	s_barrier
	s_setprio 0
	s_add_i32 vcc_hi, vcc_hi, 2
	s_add_u32 s28, s28, 0x100
	s_addc_u32 s29, s29, 0
	s_add_u32 s97, s97, 0x100
	s_addc_u32 vcc_lo, vcc_lo, 0
	s_cmp_gt_u32 vcc_hi, 29
	s_cbranch_scc0 .LBB0_315
	s_and_b64 vcc, exec, s[10:11]
	s_cbranch_vccz .LBB0_318
	s_barrier

; #define PG8_STAGE(bufoff, gbase, voff) do { _Pragma("unroll") for (int _i = 0; _i < 2; ++_i) \
;         __builtin_amdgcn_global_load_lds((const unsigned*)((const char*)(gbase) + (voff)[_i]), (PG8_LAS unsigned*)(lds + (bufoff) + ldsw + _i * 8192), 16, 0, 0); } while (0)
; #define PG8_LDA(dst, b, h) do { _Pragma("unroll") for (int m = 0; m < 4; ++m) _Pragma("unroll") for (int k = 0; k < 2; ++k) dst[m][k] = *(const PG8_LAS bf16x8*)(lds + PG8_SA(b, h) + aoff + m * 2048 + k * 1024); } while (0)
; #define PG8_LDB(dst, b, h) do { _Pragma("unroll") for (int n = 0; n < 2; ++n) _Pragma("unroll") for (int k = 0; k < 2; ++k) dst[n][k] = *(const PG8_LAS bf16x8*)(lds + PG8_SB(b, h) + boff + n * 2048 + k * 1024); } while (0)
; #define PG8_MMA(ai, bj, At, Bt) do { __builtin_amdgcn_s_setprio(1); _Pragma("unroll") for (int m = 0; m < 4; ++m) _Pragma("unroll") for (int n = 0; n < 2; ++n) _Pragma("unroll") for (int k = 0; k < 2; ++k) \
;         acc[ai][bj][m][n] = __builtin_amdgcn_mfma_f32_16x16x32_bf16(Bt[n][k], At[m][k], acc[ai][bj][m][n], 0, 0, 0); __builtin_amdgcn_s_setprio(0); } while (0)
; #define PG8_WAIT_V(n) asm volatile("s_waitcnt vmcnt(" #n ")" ::: "memory")
; #define PG8_BAR __builtin_amdgcn_s_barrier()
; template <class Epi, class Sched, bool ALIGN_EPI = false, bool SP2 = false>
; __device__ __forceinline__ void gemm_phase(PG8_LAS unsigned char* lds, const Gemm g, const Sched& S, const Epi& E) {
;     ...
;         for (int t = 0; t < nt; t += 2) {
;             const bool last = (t == nt - 2);
;             const char* a1 = cA + (size_t)(t + 1) * kstep;
;             const char* a2 = last ? nA : cA + (size_t)(t + 2) * kstep; const char* b2 = last ? nB : cB + (size_t)(t + 2) * kstep;
;             const char* a3 = a2 + kstep; const char* b3 = b2 + kstep;
;             if (last && has_next) S.a_ready(nxt);
;             if constexpr (SP2) {
;             PG8_LDB(B0, 0, 0); PG8_LDB(B1, 0, 1); PG8_SCHED; PG8_LDA(At, 0, 0); PG8_STAGE(PG8_SA(1, 1), a1 + hstepA, voffA);
;             PG8_WAIT_V(8); PG8_WAIT_L(0); PG8_BAR; PG8_MMA(0, 0, At, B0); PG8_MMA(0, 1, At, B1); PG8_BAR; PG8_SCHED;
;             PG8_LDA(At, 0, 1); PG8_STAGE(PG8_SB(0, 0), b2, voffB); PG8_STAGE(PG8_SB(0, 1), b2 + hstepB, voffB); PG8_STAGE(PG8_SA(0, 0), a2, voffA);
;             PG8_WAIT_V(8); PG8_WAIT_L(0); PG8_BAR; PG8_MMA(1, 0, At, B0); PG8_MMA(1, 1, At, B1); PG8_BAR; PG8_SCHED;
.LBB0_458:
	v_add_u32_e32 v1, s67, v202
	ds_read_b128 v[132:135], v1
	ds_read_b128 v[136:139], v1 offset:1024
	ds_read_b128 v[140:143], v1 offset:2048
	ds_read_b128 v[144:147], v1 offset:3072
	v_add_u32_e32 v1, s84, v202
	ds_read_b128 v[148:151], v1
	ds_read_b128 v[152:155], v1 offset:1024
	ds_read_b128 v[156:159], v1 offset:2048
	ds_read_b128 v[160:163], v1 offset:3072
	s_add_u32 s3, s30, 0xfff00080
	s_addc_u32 s36, s31, -1
	s_cmp_eq_u32 vcc_lo, 12
	s_cselect_b32 s39, s23, s36
	s_cselect_b32 s38, s94, s3
	s_cselect_b32 s37, s25, s97
	s_cselect_b32 s36, s95, s96
	v_lshl_add_u64 v[2:3], s[30:31], 0, v[190:191]
	s_add_i32 m0, s53, 0xc000
	ds_read_b128 v[164:167], v204
	ds_read_b128 v[168:171], v204 offset:1024
	ds_read_b128 v[172:175], v204 offset:2048
	ds_read_b128 v[176:179], v204 offset:3072
	ds_read_b128 v[206:209], v204 offset:4096
	ds_read_b128 v[210:213], v204 offset:5120
	ds_read_b128 v[214:217], v204 offset:6144
	ds_read_b128 v[218:221], v204 offset:7168
	global_load_lds_dwordx4 v[2:3], off
	v_lshl_add_u64 v[2:3], s[30:31], 0, v[192:193]
	s_add_i32 m0, s53, 0xe000
	s_nop 0
	global_load_lds_dwordx4 v[2:3], off
	s_waitcnt vmcnt(8)
	s_waitcnt lgkmcnt(0)
	s_setprio 1
	v_mfma_f32_16x16x32_bf16 v[128:131], v[132:135], v[164:167], v[128:131]
	v_mfma_f32_16x16x32_bf16 v[124:127], v[140:143], v[164:167], v[124:127]
	v_mfma_f32_16x16x32_bf16 v[120:123], v[132:135], v[172:175], v[120:123]
	v_mfma_f32_16x16x32_bf16 v[116:119], v[140:143], v[172:175], v[116:119]
	s_barrier
	v_mfma_f32_16x16x32_bf16 v[112:115], v[132:135], v[206:209], v[112:115]
	v_mfma_f32_16x16x32_bf16 v[108:111], v[140:143], v[206:209], v[108:111]
	v_mfma_f32_16x16x32_bf16 v[104:107], v[132:135], v[214:217], v[104:107]
	v_mfma_f32_16x16x32_bf16 v[100:103], v[140:143], v[214:217], v[100:103]
	v_mfma_f32_16x16x32_bf16 v[128:131], v[136:139], v[168:171], v[128:131]
	v_mfma_f32_16x16x32_bf16 v[124:127], v[144:147], v[168:171], v[124:127]
	v_mfma_f32_16x16x32_bf16 v[120:123], v[136:139], v[176:179], v[120:123]
	v_mfma_f32_16x16x32_bf16 v[116:119], v[144:147], v[176:179], v[116:119]
	v_mfma_f32_16x16x32_bf16 v[112:115], v[136:139], v[210:213], v[112:115]
	v_mfma_f32_16x16x32_bf16 v[108:111], v[144:147], v[210:213], v[108:111]
	v_mfma_f32_16x16x32_bf16 v[104:107], v[136:139], v[218:221], v[104:107]
	v_mfma_f32_16x16x32_bf16 v[100:103], v[144:147], v[218:221], v[100:103]
	v_mfma_f32_16x16x32_bf16 v[96:99], v[148:151], v[164:167], v[96:99]
	v_mfma_f32_16x16x32_bf16 v[92:95], v[156:159], v[164:167], v[92:95]
	v_mfma_f32_16x16x32_bf16 v[88:91], v[148:151], v[172:175], v[88:91]
	v_mfma_f32_16x16x32_bf16 v[84:87], v[156:159], v[172:175], v[84:87]
	v_mfma_f32_16x16x32_bf16 v[80:83], v[148:151], v[206:209], v[80:83]
	v_mfma_f32_16x16x32_bf16 v[76:79], v[156:159], v[206:209], v[76:79]
	v_mfma_f32_16x16x32_bf16 v[72:75], v[148:151], v[214:217], v[72:75]
	v_mfma_f32_16x16x32_bf16 v[68:71], v[156:159], v[214:217], v[68:71]
	v_mfma_f32_16x16x32_bf16 v[96:99], v[152:155], v[168:171], v[96:99]
	v_mfma_f32_16x16x32_bf16 v[92:95], v[160:163], v[168:171], v[92:95]
	v_mfma_f32_16x16x32_bf16 v[88:91], v[152:155], v[176:179], v[88:91]
	v_mfma_f32_16x16x32_bf16 v[84:87], v[160:163], v[176:179], v[84:87]
	v_mfma_f32_16x16x32_bf16 v[80:83], v[152:155], v[210:213], v[80:83]
	v_mfma_f32_16x16x32_bf16 v[76:79], v[160:163], v[210:213], v[76:79]
	v_mfma_f32_16x16x32_bf16 v[72:75], v[152:155], v[218:221], v[72:75]
	v_mfma_f32_16x16x32_bf16 v[68:71], v[160:163], v[218:221], v[68:71]
	s_barrier
	s_setprio 0
	s_add_i32 s3, s67, s52
	v_lshl_add_u64 v[198:199], s[36:37], 0, v[184:185]
	s_mov_b32 m0, s3
	ds_read_b128 v[164:167], v204 offset:16384
	ds_read_b128 v[168:171], v204 offset:17408
	ds_read_b128 v[172:175], v204 offset:18432
	ds_read_b128 v[176:179], v204 offset:19456
	ds_read_b128 v[206:209], v204 offset:20480
	ds_read_b128 v[210:213], v204 offset:21504
	ds_read_b128 v[214:217], v204 offset:22528
	ds_read_b128 v[218:221], v204 offset:23552
	global_load_lds_dwordx4 v[198:199], off
	s_add_i32 m0, s3, 0x2000
	s_add_u32 s44, s36, 0x40000
	v_lshl_add_u64 v[222:223], s[36:37], 0, v[188:189]
	s_addc_u32 s45, s37, 0
	s_add_i32 s3, s84, s52
	global_load_lds_dwordx4 v[222:223], off
	v_lshl_add_u64 v[2:3], s[44:45], 0, v[184:185]
	s_mov_b32 m0, s3
	v_lshl_add_u64 v[224:225], s[38:39], 0, v[182:183]
	global_load_lds_dwordx4 v[2:3], off
	v_lshl_add_u64 v[2:3], s[44:45], 0, v[188:189]
	s_add_i32 m0, s3, 0x2000
	v_lshl_add_u64 v[226:227], s[38:39], 0, v[186:187]
	global_load_lds_dwordx4 v[2:3], off
	s_mov_b32 m0, s53
	s_nop 0
	global_load_lds_dwordx4 v[224:225], off
	s_mov_b32 m0, s56
	s_nop 0
	global_load_lds_dwordx4 v[226:227], off
	s_waitcnt vmcnt(8)
	s_waitcnt lgkmcnt(0)
	s_setprio 1
	v_mfma_f32_16x16x32_bf16 v[64:67], v[132:135], v[164:167], v[64:67]
	v_mfma_f32_16x16x32_bf16 v[60:63], v[140:143], v[164:167], v[60:63]
	v_mfma_f32_16x16x32_bf16 v[56:59], v[132:135], v[172:175], v[56:59]
	v_mfma_f32_16x16x32_bf16 v[52:55], v[140:143], v[172:175], v[52:55]
	s_barrier
; #define PG8_STAGE(bufoff, gbase, voff) do { _Pragma("unroll") for (int _i = 0; _i < 2; ++_i) \
;         __builtin_amdgcn_global_load_lds((const unsigned*)((const char*)(gbase) + (voff)[_i]), (PG8_LAS unsigned*)(lds + (bufoff) + ldsw + _i * 8192), 16, 0, 0); } while (0)
; #define PG8_LDA(dst, b, h) do { _Pragma("unroll") for (int m = 0; m < 4; ++m) _Pragma("unroll") for (int k = 0; k < 2; ++k) dst[m][k] = *(const PG8_LAS bf16x8*)(lds + PG8_SA(b, h) + aoff + m * 2048 + k * 1024); } while (0)
; #define PG8_LDB(dst, b, h) do { _Pragma("unroll") for (int n = 0; n < 2; ++n) _Pragma("unroll") for (int k = 0; k < 2; ++k) dst[n][k] = *(const PG8_LAS bf16x8*)(lds + PG8_SB(b, h) + boff + n * 2048 + k * 1024); } while (0)
; #define PG8_MMA(ai, bj, At, Bt) do { __builtin_amdgcn_s_setprio(1); _Pragma("unroll") for (int m = 0; m < 4; ++m) _Pragma("unroll") for (int n = 0; n < 2; ++n) _Pragma("unroll") for (int k = 0; k < 2; ++k) \
;         acc[ai][bj][m][n] = __builtin_amdgcn_mfma_f32_16x16x32_bf16(Bt[n][k], At[m][k], acc[ai][bj][m][n], 0, 0, 0); __builtin_amdgcn_s_setprio(0); } while (0)
; #define PG8_WAIT_V(n) asm volatile("s_waitcnt vmcnt(" #n ")" ::: "memory")
; #define PG8_WAIT_L(n) asm volatile("s_waitcnt lgkmcnt(" #n ")" ::: "memory")
; #define PG8_BAR __builtin_amdgcn_s_barrier()
; #define PG8_SCHED __builtin_amdgcn_sched_barrier(0)
; template <class Epi, class Sched, bool ALIGN_EPI = false, bool SP2 = false>
; __device__ __forceinline__ void gemm_phase(PG8_LAS unsigned char* lds, const Gemm g, const Sched& S, const Epi& E) {
;     ...
;             PG8_WAIT_V(8); PG8_WAIT_L(0); PG8_BAR; PG8_MMA(1, 0, At, B0); PG8_MMA(1, 1, At, B1); PG8_BAR; PG8_SCHED;
;             PG8_LDB(B0, 1, 0); PG8_LDB(B1, 1, 1); PG8_SCHED; PG8_LDA(At, 1, 0); PG8_STAGE(PG8_SA(0, 1), a2 + hstepA, voffA);
;             PG8_WAIT_V(8); PG8_WAIT_L(0); PG8_BAR; PG8_MMA(0, 0, At, B0); PG8_MMA(0, 1, At, B1); PG8_BAR; PG8_SCHED;
	v_mfma_f32_16x16x32_bf16 v[48:51], v[132:135], v[206:209], v[48:51]
	v_mfma_f32_16x16x32_bf16 v[44:47], v[140:143], v[206:209], v[44:47]
	v_mfma_f32_16x16x32_bf16 v[40:43], v[132:135], v[214:217], v[40:43]
	v_mfma_f32_16x16x32_bf16 v[36:39], v[140:143], v[214:217], v[36:39]
	v_mfma_f32_16x16x32_bf16 v[64:67], v[136:139], v[168:171], v[64:67]
	v_mfma_f32_16x16x32_bf16 v[60:63], v[144:147], v[168:171], v[60:63]
	v_mfma_f32_16x16x32_bf16 v[56:59], v[136:139], v[176:179], v[56:59]
	v_mfma_f32_16x16x32_bf16 v[52:55], v[144:147], v[176:179], v[52:55]
	v_mfma_f32_16x16x32_bf16 v[48:51], v[136:139], v[210:213], v[48:51]
	v_mfma_f32_16x16x32_bf16 v[44:47], v[144:147], v[210:213], v[44:47]
	v_mfma_f32_16x16x32_bf16 v[40:43], v[136:139], v[218:221], v[40:43]
	v_mfma_f32_16x16x32_bf16 v[36:39], v[144:147], v[218:221], v[36:39]
	v_mfma_f32_16x16x32_bf16 v[32:35], v[148:151], v[164:167], v[32:35]
	v_mfma_f32_16x16x32_bf16 v[28:31], v[156:159], v[164:167], v[28:31]
	v_mfma_f32_16x16x32_bf16 v[24:27], v[148:151], v[172:175], v[24:27]
	v_mfma_f32_16x16x32_bf16 v[20:23], v[156:159], v[172:175], v[20:23]
	v_mfma_f32_16x16x32_bf16 v[16:19], v[148:151], v[206:209], v[16:19]
	v_mfma_f32_16x16x32_bf16 v[12:15], v[156:159], v[206:209], v[12:15]
	v_mfma_f32_16x16x32_bf16 v[8:11], v[148:151], v[214:217], v[8:11]
	v_mfma_f32_16x16x32_bf16 v[2:5], v[156:159], v[214:217], v[4:7]
	v_mfma_f32_16x16x32_bf16 v[32:35], v[152:155], v[168:171], v[32:35]
	v_mfma_f32_16x16x32_bf16 v[28:31], v[160:163], v[168:171], v[28:31]
	v_mfma_f32_16x16x32_bf16 v[24:27], v[152:155], v[176:179], v[24:27]
	v_mfma_f32_16x16x32_bf16 v[20:23], v[160:163], v[176:179], v[20:23]
	v_mfma_f32_16x16x32_bf16 v[16:19], v[152:155], v[210:213], v[16:19]
	v_mfma_f32_16x16x32_bf16 v[12:15], v[160:163], v[210:213], v[12:15]
	v_mfma_f32_16x16x32_bf16 v[8:11], v[152:155], v[218:221], v[8:11]
	v_mfma_f32_16x16x32_bf16 v[2:5], v[160:163], v[218:221], v[2:5]
	s_barrier
	s_setprio 0
	s_add_i32 s3, 0, 0x18000
	v_add_u32_e32 v1, s3, v202
	s_add_i32 s44, 0, 0x1c000
	ds_read_b128 v[132:135], v1
	ds_read_b128 v[136:139], v1 offset:1024
	ds_read_b128 v[140:143], v1 offset:2048
	ds_read_b128 v[144:147], v1 offset:3072
	v_add_u32_e32 v1, s44, v202
	ds_read_b128 v[148:151], v1
	ds_read_b128 v[152:155], v1 offset:1024
	ds_read_b128 v[156:159], v1 offset:2048
	ds_read_b128 v[160:163], v1 offset:3072
	s_add_u32 s38, s38, 0x100000
	s_addc_u32 s39, s39, 0
	s_mov_b32 m0, s57
	v_lshl_add_u64 v[6:7], s[38:39], 0, v[182:183]
	ds_read_b128 v[164:167], v204 offset:32768
	ds_read_b128 v[168:171], v204 offset:33792
	ds_read_b128 v[172:175], v204 offset:34816
	ds_read_b128 v[176:179], v204 offset:35840
	ds_read_b128 v[206:209], v204 offset:36864
	ds_read_b128 v[210:213], v204 offset:37888
	ds_read_b128 v[214:217], v204 offset:38912
	ds_read_b128 v[218:221], v204 offset:39936
	global_load_lds_dwordx4 v[6:7], off
	v_lshl_add_u64 v[6:7], s[38:39], 0, v[186:187]
	s_mov_b32 m0, s62
	s_nop 0
	global_load_lds_dwordx4 v[6:7], off
	s_waitcnt vmcnt(8)
	s_waitcnt lgkmcnt(0)
	s_setprio 1
	v_mfma_f32_16x16x32_bf16 v[128:131], v[132:135], v[164:167], v[128:131]
	v_mfma_f32_16x16x32_bf16 v[124:127], v[140:143], v[164:167], v[124:127]
	v_mfma_f32_16x16x32_bf16 v[120:123], v[132:135], v[172:175], v[120:123]
	v_mfma_f32_16x16x32_bf16 v[116:119], v[140:143], v[172:175], v[116:119]
	s_barrier
	v_mfma_f32_16x16x32_bf16 v[112:115], v[132:135], v[206:209], v[112:115]
	v_mfma_f32_16x16x32_bf16 v[108:111], v[140:143], v[206:209], v[108:111]
	v_mfma_f32_16x16x32_bf16 v[104:107], v[132:135], v[214:217], v[104:107]
	v_mfma_f32_16x16x32_bf16 v[100:103], v[140:143], v[214:217], v[100:103]
	v_mfma_f32_16x16x32_bf16 v[128:131], v[136:139], v[168:171], v[128:131]
	v_mfma_f32_16x16x32_bf16 v[124:127], v[144:147], v[168:171], v[124:127]
	v_mfma_f32_16x16x32_bf16 v[120:123], v[136:139], v[176:179], v[120:123]
	v_mfma_f32_16x16x32_bf16 v[116:119], v[144:147], v[176:179], v[116:119]
	v_mfma_f32_16x16x32_bf16 v[112:115], v[136:139], v[210:213], v[112:115]
	v_mfma_f32_16x16x32_bf16 v[108:111], v[144:147], v[210:213], v[108:111]
	v_mfma_f32_16x16x32_bf16 v[104:107], v[136:139], v[218:221], v[104:107]
	v_mfma_f32_16x16x32_bf16 v[100:103], v[144:147], v[218:221], v[100:103]
	v_mfma_f32_16x16x32_bf16 v[96:99], v[148:151], v[164:167], v[96:99]
	v_mfma_f32_16x16x32_bf16 v[92:95], v[156:159], v[164:167], v[92:95]
	v_mfma_f32_16x16x32_bf16 v[88:91], v[148:151], v[172:175], v[88:91]
	v_mfma_f32_16x16x32_bf16 v[84:87], v[156:159], v[172:175], v[84:87]
	v_mfma_f32_16x16x32_bf16 v[80:83], v[148:151], v[206:209], v[80:83]
	v_mfma_f32_16x16x32_bf16 v[76:79], v[156:159], v[206:209], v[76:79]
	v_mfma_f32_16x16x32_bf16 v[72:75], v[148:151], v[214:217], v[72:75]
	v_mfma_f32_16x16x32_bf16 v[68:71], v[156:159], v[214:217], v[68:71]
	v_mfma_f32_16x16x32_bf16 v[96:99], v[152:155], v[168:171], v[96:99]
	v_mfma_f32_16x16x32_bf16 v[92:95], v[160:163], v[168:171], v[92:95]
	v_mfma_f32_16x16x32_bf16 v[88:91], v[152:155], v[176:179], v[88:91]
	v_mfma_f32_16x16x32_bf16 v[84:87], v[160:163], v[176:179], v[84:87]
	v_mfma_f32_16x16x32_bf16 v[80:83], v[152:155], v[210:213], v[80:83]
	v_mfma_f32_16x16x32_bf16 v[76:79], v[160:163], v[210:213], v[76:79]
	v_mfma_f32_16x16x32_bf16 v[72:75], v[152:155], v[218:221], v[72:75]
	v_mfma_f32_16x16x32_bf16 v[68:71], v[160:163], v[218:221], v[68:71]
	s_barrier
; #define PG8_STAGE(bufoff, gbase, voff) do { _Pragma("unroll") for (int _i = 0; _i < 2; ++_i) \
;         __builtin_amdgcn_global_load_lds((const unsigned*)((const char*)(gbase) + (voff)[_i]), (PG8_LAS unsigned*)(lds + (bufoff) + ldsw + _i * 8192), 16, 0, 0); } while (0)
; #define PG8_LDA(dst, b, h) do { _Pragma("unroll") for (int m = 0; m < 4; ++m) _Pragma("unroll") for (int k = 0; k < 2; ++k) dst[m][k] = *(const PG8_LAS bf16x8*)(lds + PG8_SA(b, h) + aoff + m * 2048 + k * 1024); } while (0)
; #define PG8_MMA(ai, bj, At, Bt) do { __builtin_amdgcn_s_setprio(1); _Pragma("unroll") for (int m = 0; m < 4; ++m) _Pragma("unroll") for (int n = 0; n < 2; ++n) _Pragma("unroll") for (int k = 0; k < 2; ++k) \
;         acc[ai][bj][m][n] = __builtin_amdgcn_mfma_f32_16x16x32_bf16(Bt[n][k], At[m][k], acc[ai][bj][m][n], 0, 0, 0); __builtin_amdgcn_s_setprio(0); } while (0)
; #define PG8_WAIT_V(n) asm volatile("s_waitcnt vmcnt(" #n ")" ::: "memory")
; #define PG8_WAIT_L(n) asm volatile("s_waitcnt lgkmcnt(" #n ")" ::: "memory")
; #define PG8_BAR __builtin_amdgcn_s_barrier()
; #define PG8_SCHED __builtin_amdgcn_sched_barrier(0)
; template <class Epi, class Sched, bool ALIGN_EPI = false, bool SP2 = false>
; __device__ __forceinline__ void gemm_phase(PG8_LAS unsigned char* lds, const Gemm g, const Sched& S, const Epi& E) {
;     ...
;             PG8_WAIT_V(8); PG8_WAIT_L(0); PG8_BAR; PG8_MMA(0, 0, At, B0); PG8_MMA(0, 1, At, B1); PG8_BAR; PG8_SCHED;
;             PG8_LDA(At, 1, 1); PG8_STAGE(PG8_SB(1, 0), b3, voffB); PG8_STAGE(PG8_SB(1, 1), b3 + hstepB, voffB); PG8_STAGE(PG8_SA(1, 0), a3, voffA);
;             PG8_WAIT_V(8); PG8_WAIT_L(0); PG8_BAR; PG8_MMA(1, 0, At, B0); PG8_MMA(1, 1, At, B1); PG8_BAR; PG8_SCHED;
;     ...
;         if constexpr (ALIGN_EPI) { if (wr == 0) PG8_BAR; }
	s_setprio 0
	s_add_i32 s3, s3, s52
	v_lshl_add_u64 v[6:7], v[198:199], 0, s[8:9]
	s_mov_b32 m0, s3
	ds_read_b128 v[164:167], v204 offset:49152
	ds_read_b128 v[168:171], v204 offset:50176
	ds_read_b128 v[172:175], v204 offset:51200
	ds_read_b128 v[176:179], v204 offset:52224
	ds_read_b128 v[206:209], v204 offset:53248
	ds_read_b128 v[210:213], v204 offset:54272
	ds_read_b128 v[214:217], v204 offset:55296
	ds_read_b128 v[218:221], v204 offset:56320
	global_load_lds_dwordx4 v[6:7], off
	s_add_i32 m0, s3, 0x2000
	s_add_u32 s36, s36, 0x40080
	v_lshl_add_u64 v[6:7], v[222:223], 0, s[8:9]
	s_addc_u32 s37, s37, 0
	s_add_i32 s3, s44, s52
	global_load_lds_dwordx4 v[6:7], off
	v_lshl_add_u64 v[6:7], s[36:37], 0, v[184:185]
	s_mov_b32 m0, s3
	s_nop 0
	global_load_lds_dwordx4 v[6:7], off
	v_lshl_add_u64 v[6:7], s[36:37], 0, v[188:189]
	s_add_i32 m0, s3, 0x2000
	s_nop 0
	global_load_lds_dwordx4 v[6:7], off
	v_lshl_add_u64 v[6:7], v[224:225], 0, s[8:9]
	s_mov_b32 m0, s65
	s_nop 0
	global_load_lds_dwordx4 v[6:7], off
	v_lshl_add_u64 v[6:7], v[226:227], 0, s[8:9]
	s_mov_b32 m0, s66
	s_nop 0
	global_load_lds_dwordx4 v[6:7], off
	s_waitcnt vmcnt(8)
	s_waitcnt lgkmcnt(0)
	s_setprio 1
	v_mfma_f32_16x16x32_bf16 v[64:67], v[132:135], v[164:167], v[64:67]
	v_mfma_f32_16x16x32_bf16 v[60:63], v[140:143], v[164:167], v[60:63]
	v_mfma_f32_16x16x32_bf16 v[56:59], v[132:135], v[172:175], v[56:59]
	v_mfma_f32_16x16x32_bf16 v[52:55], v[140:143], v[172:175], v[52:55]
	s_barrier
	v_mfma_f32_16x16x32_bf16 v[48:51], v[132:135], v[206:209], v[48:51]
	v_mfma_f32_16x16x32_bf16 v[44:47], v[140:143], v[206:209], v[44:47]
	v_mfma_f32_16x16x32_bf16 v[40:43], v[132:135], v[214:217], v[40:43]
	v_mfma_f32_16x16x32_bf16 v[36:39], v[140:143], v[214:217], v[36:39]
	v_mfma_f32_16x16x32_bf16 v[64:67], v[136:139], v[168:171], v[64:67]
	v_mfma_f32_16x16x32_bf16 v[60:63], v[144:147], v[168:171], v[60:63]
	v_mfma_f32_16x16x32_bf16 v[56:59], v[136:139], v[176:179], v[56:59]
	v_mfma_f32_16x16x32_bf16 v[52:55], v[144:147], v[176:179], v[52:55]
	v_mfma_f32_16x16x32_bf16 v[48:51], v[136:139], v[210:213], v[48:51]
	v_mfma_f32_16x16x32_bf16 v[44:47], v[144:147], v[210:213], v[44:47]
	v_mfma_f32_16x16x32_bf16 v[40:43], v[136:139], v[218:221], v[40:43]
	v_mfma_f32_16x16x32_bf16 v[36:39], v[144:147], v[218:221], v[36:39]
	v_mfma_f32_16x16x32_bf16 v[32:35], v[148:151], v[164:167], v[32:35]
	v_mfma_f32_16x16x32_bf16 v[28:31], v[156:159], v[164:167], v[28:31]
	v_mfma_f32_16x16x32_bf16 v[24:27], v[148:151], v[172:175], v[24:27]
	v_mfma_f32_16x16x32_bf16 v[20:23], v[156:159], v[172:175], v[20:23]
	v_mfma_f32_16x16x32_bf16 v[16:19], v[148:151], v[206:209], v[16:19]
	v_mfma_f32_16x16x32_bf16 v[12:15], v[156:159], v[206:209], v[12:15]
	v_mfma_f32_16x16x32_bf16 v[6:9], v[148:151], v[214:217], v[8:11]
	v_mfma_f32_16x16x32_bf16 v[2:5], v[156:159], v[214:217], v[2:5]
	v_mfma_f32_16x16x32_bf16 v[32:35], v[152:155], v[168:171], v[32:35]
	v_mfma_f32_16x16x32_bf16 v[28:31], v[160:163], v[168:171], v[28:31]
	v_mfma_f32_16x16x32_bf16 v[24:27], v[152:155], v[176:179], v[24:27]
	v_mfma_f32_16x16x32_bf16 v[20:23], v[160:163], v[176:179], v[20:23]
	v_mfma_f32_16x16x32_bf16 v[16:19], v[152:155], v[210:213], v[16:19]
	v_mfma_f32_16x16x32_bf16 v[12:15], v[160:163], v[210:213], v[12:15]
	v_mfma_f32_16x16x32_bf16 v[8:11], v[152:155], v[218:221], v[6:9]
	v_mfma_f32_16x16x32_bf16 v[4:7], v[160:163], v[218:221], v[2:5]
	s_barrier
	s_setprio 0
	s_add_i32 vcc_lo, vcc_lo, 2
	s_add_u32 s30, s30, 0x100
	s_addc_u32 s31, s31, 0
	s_add_u32 s96, s96, 0x100
	s_addc_u32 s97, s97, 0
	s_cmp_gt_u32 vcc_lo, 13
	s_cbranch_scc0 .LBB0_458
	s_and_b64 vcc, exec, s[10:11]
	s_cbranch_vccz .LBB0_461
	s_barrier

; #define PG8_STAGE(bufoff, gbase, voff) do { _Pragma("unroll") for (int _i = 0; _i < 2; ++_i) \
;         __builtin_amdgcn_global_load_lds((const unsigned*)((const char*)(gbase) + (voff)[_i]), (PG8_LAS unsigned*)(lds + (bufoff) + ldsw + _i * 8192), 16, 0, 0); } while (0)
; #define PG8_LDA(dst, b, h) do { _Pragma("unroll") for (int m = 0; m < 4; ++m) _Pragma("unroll") for (int k = 0; k < 2; ++k) dst[m][k] = *(const PG8_LAS bf16x8*)(lds + PG8_SA(b, h) + aoff + m * 2048 + k * 1024); } while (0)
; #define PG8_LDB(dst, b, h) do { _Pragma("unroll") for (int n = 0; n < 2; ++n) _Pragma("unroll") for (int k = 0; k < 2; ++k) dst[n][k] = *(const PG8_LAS bf16x8*)(lds + PG8_SB(b, h) + boff + n * 2048 + k * 1024); } while (0)
; #define PG8_MMA(ai, bj, At, Bt) do { __builtin_amdgcn_s_setprio(1); _Pragma("unroll") for (int m = 0; m < 4; ++m) _Pragma("unroll") for (int n = 0; n < 2; ++n) _Pragma("unroll") for (int k = 0; k < 2; ++k) \
;         acc[ai][bj][m][n] = __builtin_amdgcn_mfma_f32_16x16x32_bf16(Bt[n][k], At[m][k], acc[ai][bj][m][n], 0, 0, 0); __builtin_amdgcn_s_setprio(0); } while (0)
; #define PG8_WAIT_V(n) asm volatile("s_waitcnt vmcnt(" #n ")" ::: "memory")
; #define PG8_BAR __builtin_amdgcn_s_barrier()
; template <class Epi, class Sched, bool ALIGN_EPI = false, bool SP2 = false>
; __device__ __forceinline__ void gemm_phase(PG8_LAS unsigned char* lds, const Gemm g, const Sched& S, const Epi& E) {
;     ...
;         for (int t = 0; t < nt; t += 2) {
;             const bool last = (t == nt - 2);
;             const char* a1 = cA + (size_t)(t + 1) * kstep;
;             const char* a2 = last ? nA : cA + (size_t)(t + 2) * kstep; const char* b2 = last ? nB : cB + (size_t)(t + 2) * kstep;
;             const char* a3 = a2 + kstep; const char* b3 = b2 + kstep;
;             if (last && has_next) S.a_ready(nxt);
;             if constexpr (SP2) {
;             PG8_LDB(B0, 0, 0); PG8_LDB(B1, 0, 1); PG8_SCHED; PG8_LDA(At, 0, 0); PG8_STAGE(PG8_SA(1, 1), a1 + hstepA, voffA);
;             PG8_WAIT_V(8); PG8_WAIT_L(0); PG8_BAR; PG8_MMA(0, 0, At, B0); PG8_MMA(0, 1, At, B1); PG8_BAR; PG8_SCHED;
;             PG8_LDA(At, 0, 1); PG8_STAGE(PG8_SB(0, 0), b2, voffB); PG8_STAGE(PG8_SB(0, 1), b2 + hstepB, voffB); PG8_STAGE(PG8_SA(0, 0), a2, voffA);
;             PG8_WAIT_V(8); PG8_WAIT_L(0); PG8_BAR; PG8_MMA(1, 0, At, B0); PG8_MMA(1, 1, At, B1); PG8_BAR; PG8_SCHED;
.LBB0_540:
	ds_read_b128 v[150:153], v147
	ds_read_b128 v[154:157], v147 offset:1024
	ds_read_b128 v[158:161], v147 offset:2048
	ds_read_b128 v[162:165], v147 offset:3072
	ds_read_b128 v[166:169], v148
	ds_read_b128 v[170:173], v148 offset:1024
	ds_read_b128 v[174:177], v148 offset:2048
	ds_read_b128 v[182:185], v148 offset:3072
	s_add_u32 s3, s30, 0xfff80080
	s_addc_u32 s34, s31, -1
	s_cmp_eq_u32 s88, 28
	s_cselect_b32 s37, s23, s34
	s_cselect_b32 s36, s84, s3
	s_cselect_b32 s35, s25, s87
	s_cselect_b32 s34, s85, s86
	v_lshl_add_u64 v[178:179], s[30:31], 0, v[136:137]
	s_add_i32 m0, s21, 0xc000
	ds_read_b128 v[186:189], v149
	ds_read_b128 v[190:193], v149 offset:1024
	ds_read_b128 v[194:197], v149 offset:2048
	ds_read_b128 v[202:205], v149 offset:3072
	ds_read_b128 v[206:209], v149 offset:4096
	ds_read_b128 v[210:213], v149 offset:5120
	ds_read_b128 v[214:217], v149 offset:6144
	ds_read_b128 v[218:221], v149 offset:7168
	global_load_lds_dwordx4 v[178:179], off
	v_lshl_add_u64 v[178:179], s[30:31], 0, v[138:139]
	s_add_i32 m0, s21, 0xe000
	s_nop 0
	global_load_lds_dwordx4 v[178:179], off
	s_waitcnt vmcnt(8)
	s_waitcnt lgkmcnt(0)
	s_setprio 1
	v_mfma_f32_16x16x32_bf16 v[124:127], v[150:153], v[186:189], v[124:127]
	v_mfma_f32_16x16x32_bf16 v[120:123], v[158:161], v[186:189], v[120:123]
	v_mfma_f32_16x16x32_bf16 v[116:119], v[150:153], v[194:197], v[116:119]
	v_mfma_f32_16x16x32_bf16 v[112:115], v[158:161], v[194:197], v[112:115]
	s_barrier
	v_mfma_f32_16x16x32_bf16 v[100:103], v[150:153], v[206:209], v[100:103]
	v_mfma_f32_16x16x32_bf16 v[96:99], v[158:161], v[206:209], v[96:99]
	v_mfma_f32_16x16x32_bf16 v[84:87], v[150:153], v[214:217], v[84:87]
	v_mfma_f32_16x16x32_bf16 v[80:83], v[158:161], v[214:217], v[80:83]
	v_mfma_f32_16x16x32_bf16 v[124:127], v[154:157], v[190:193], v[124:127]
	v_mfma_f32_16x16x32_bf16 v[120:123], v[162:165], v[190:193], v[120:123]
	v_mfma_f32_16x16x32_bf16 v[116:119], v[154:157], v[202:205], v[116:119]
	v_mfma_f32_16x16x32_bf16 v[112:115], v[162:165], v[202:205], v[112:115]
	v_mfma_f32_16x16x32_bf16 v[100:103], v[154:157], v[210:213], v[100:103]
	v_mfma_f32_16x16x32_bf16 v[96:99], v[162:165], v[210:213], v[96:99]
	v_mfma_f32_16x16x32_bf16 v[84:87], v[154:157], v[218:221], v[84:87]
	v_mfma_f32_16x16x32_bf16 v[80:83], v[162:165], v[218:221], v[80:83]
	v_mfma_f32_16x16x32_bf16 v[108:111], v[166:169], v[186:189], v[108:111]
	v_mfma_f32_16x16x32_bf16 v[104:107], v[174:177], v[186:189], v[104:107]
	v_mfma_f32_16x16x32_bf16 v[92:95], v[166:169], v[194:197], v[92:95]
	v_mfma_f32_16x16x32_bf16 v[88:91], v[174:177], v[194:197], v[88:91]
	v_mfma_f32_16x16x32_bf16 v[76:79], v[166:169], v[206:209], v[76:79]
	v_mfma_f32_16x16x32_bf16 v[72:75], v[174:177], v[206:209], v[72:75]
	v_mfma_f32_16x16x32_bf16 v[68:71], v[166:169], v[214:217], v[68:71]
	v_mfma_f32_16x16x32_bf16 v[64:67], v[174:177], v[214:217], v[64:67]
	v_mfma_f32_16x16x32_bf16 v[108:111], v[170:173], v[190:193], v[108:111]
	v_mfma_f32_16x16x32_bf16 v[104:107], v[182:185], v[190:193], v[104:107]
	v_mfma_f32_16x16x32_bf16 v[92:95], v[170:173], v[202:205], v[92:95]
	v_mfma_f32_16x16x32_bf16 v[88:91], v[182:185], v[202:205], v[88:91]
	v_mfma_f32_16x16x32_bf16 v[76:79], v[170:173], v[210:213], v[76:79]
	v_mfma_f32_16x16x32_bf16 v[72:75], v[182:185], v[210:213], v[72:75]
	v_mfma_f32_16x16x32_bf16 v[68:71], v[170:173], v[218:221], v[68:71]
	v_mfma_f32_16x16x32_bf16 v[64:67], v[182:185], v[218:221], v[64:67]
	s_barrier
	s_setprio 0
	s_add_i32 s3, s65, s39
	v_lshl_add_u64 v[178:179], s[34:35], 0, v[130:131]
	s_mov_b32 m0, s3
	ds_read_b128 v[186:189], v149 offset:16384
	ds_read_b128 v[190:193], v149 offset:17408
	ds_read_b128 v[194:197], v149 offset:18432
	ds_read_b128 v[202:205], v149 offset:19456
	ds_read_b128 v[206:209], v149 offset:20480
	ds_read_b128 v[210:213], v149 offset:21504
	ds_read_b128 v[214:217], v149 offset:22528
	ds_read_b128 v[218:221], v149 offset:23552
	global_load_lds_dwordx4 v[178:179], off
	s_add_i32 m0, s3, 0x2000
	s_add_u32 s44, s34, 0x80000
	v_lshl_add_u64 v[198:199], s[34:35], 0, v[134:135]
	s_addc_u32 s45, s35, 0
	s_add_i32 s3, s66, s39
	global_load_lds_dwordx4 v[198:199], off
	v_lshl_add_u64 v[222:223], s[44:45], 0, v[130:131]
	s_mov_b32 m0, s3
	v_lshl_add_u64 v[224:225], s[36:37], 0, v[132:133]
	global_load_lds_dwordx4 v[222:223], off
	v_lshl_add_u64 v[222:223], s[44:45], 0, v[134:135]
	s_add_i32 m0, s3, 0x2000
	s_nop 0
	global_load_lds_dwordx4 v[222:223], off
	v_lshl_add_u64 v[222:223], s[36:37], 0, v[128:129]
	s_mov_b32 m0, s21
	s_nop 0
	global_load_lds_dwordx4 v[222:223], off
	s_mov_b32 m0, s43
	s_nop 0
	global_load_lds_dwordx4 v[224:225], off
	s_waitcnt vmcnt(8)
	s_waitcnt lgkmcnt(0)
	s_setprio 1
	v_mfma_f32_16x16x32_bf16 v[60:63], v[150:153], v[186:189], v[60:63]
	v_mfma_f32_16x16x32_bf16 v[56:59], v[158:161], v[186:189], v[56:59]
	v_mfma_f32_16x16x32_bf16 v[52:55], v[150:153], v[194:197], v[52:55]
	v_mfma_f32_16x16x32_bf16 v[48:51], v[158:161], v[194:197], v[48:51]
	s_barrier
; #define PG8_STAGE(bufoff, gbase, voff) do { _Pragma("unroll") for (int _i = 0; _i < 2; ++_i) \
;         __builtin_amdgcn_global_load_lds((const unsigned*)((const char*)(gbase) + (voff)[_i]), (PG8_LAS unsigned*)(lds + (bufoff) + ldsw + _i * 8192), 16, 0, 0); } while (0)
; #define PG8_LDA(dst, b, h) do { _Pragma("unroll") for (int m = 0; m < 4; ++m) _Pragma("unroll") for (int k = 0; k < 2; ++k) dst[m][k] = *(const PG8_LAS bf16x8*)(lds + PG8_SA(b, h) + aoff + m * 2048 + k * 1024); } while (0)
; #define PG8_LDB(dst, b, h) do { _Pragma("unroll") for (int n = 0; n < 2; ++n) _Pragma("unroll") for (int k = 0; k < 2; ++k) dst[n][k] = *(const PG8_LAS bf16x8*)(lds + PG8_SB(b, h) + boff + n * 2048 + k * 1024); } while (0)
; #define PG8_MMA(ai, bj, At, Bt) do { __builtin_amdgcn_s_setprio(1); _Pragma("unroll") for (int m = 0; m < 4; ++m) _Pragma("unroll") for (int n = 0; n < 2; ++n) _Pragma("unroll") for (int k = 0; k < 2; ++k) \
;         acc[ai][bj][m][n] = __builtin_amdgcn_mfma_f32_16x16x32_bf16(Bt[n][k], At[m][k], acc[ai][bj][m][n], 0, 0, 0); __builtin_amdgcn_s_setprio(0); } while (0)
; #define PG8_WAIT_V(n) asm volatile("s_waitcnt vmcnt(" #n ")" ::: "memory")
; #define PG8_WAIT_L(n) asm volatile("s_waitcnt lgkmcnt(" #n ")" ::: "memory")
; #define PG8_BAR __builtin_amdgcn_s_barrier()
; #define PG8_SCHED __builtin_amdgcn_sched_barrier(0)
; template <class Epi, class Sched, bool ALIGN_EPI = false, bool SP2 = false>
; __device__ __forceinline__ void gemm_phase(PG8_LAS unsigned char* lds, const Gemm g, const Sched& S, const Epi& E) {
;     ...
;             PG8_WAIT_V(8); PG8_WAIT_L(0); PG8_BAR; PG8_MMA(1, 0, At, B0); PG8_MMA(1, 1, At, B1); PG8_BAR; PG8_SCHED;
;             PG8_LDB(B0, 1, 0); PG8_LDB(B1, 1, 1); PG8_SCHED; PG8_LDA(At, 1, 0); PG8_STAGE(PG8_SA(0, 1), a2 + hstepA, voffA);
;             PG8_WAIT_V(8); PG8_WAIT_L(0); PG8_BAR; PG8_MMA(0, 0, At, B0); PG8_MMA(0, 1, At, B1); PG8_BAR; PG8_SCHED;
	v_mfma_f32_16x16x32_bf16 v[36:39], v[150:153], v[206:209], v[36:39]
	v_mfma_f32_16x16x32_bf16 v[32:35], v[158:161], v[206:209], v[32:35]
	v_mfma_f32_16x16x32_bf16 v[20:23], v[150:153], v[214:217], v[20:23]
	v_mfma_f32_16x16x32_bf16 v[16:19], v[158:161], v[214:217], v[16:19]
	v_mfma_f32_16x16x32_bf16 v[60:63], v[154:157], v[190:193], v[60:63]
	v_mfma_f32_16x16x32_bf16 v[56:59], v[162:165], v[190:193], v[56:59]
	v_mfma_f32_16x16x32_bf16 v[52:55], v[154:157], v[202:205], v[52:55]
	v_mfma_f32_16x16x32_bf16 v[48:51], v[162:165], v[202:205], v[48:51]
	v_mfma_f32_16x16x32_bf16 v[36:39], v[154:157], v[210:213], v[36:39]
	v_mfma_f32_16x16x32_bf16 v[32:35], v[162:165], v[210:213], v[32:35]
	v_mfma_f32_16x16x32_bf16 v[20:23], v[154:157], v[218:221], v[20:23]
	v_mfma_f32_16x16x32_bf16 v[16:19], v[162:165], v[218:221], v[16:19]
	v_mfma_f32_16x16x32_bf16 v[44:47], v[166:169], v[186:189], v[44:47]
	v_mfma_f32_16x16x32_bf16 v[40:43], v[174:177], v[186:189], v[40:43]
	v_mfma_f32_16x16x32_bf16 v[28:31], v[166:169], v[194:197], v[28:31]
	v_mfma_f32_16x16x32_bf16 v[24:27], v[174:177], v[194:197], v[24:27]
	v_mfma_f32_16x16x32_bf16 v[12:15], v[166:169], v[206:209], v[12:15]
	v_mfma_f32_16x16x32_bf16 v[8:11], v[174:177], v[206:209], v[8:11]
	v_mfma_f32_16x16x32_bf16 v[4:7], v[166:169], v[214:217], v[4:7]
	v_mfma_f32_16x16x32_bf16 v[0:3], v[174:177], v[214:217], v[0:3]
	v_mfma_f32_16x16x32_bf16 v[44:47], v[170:173], v[190:193], v[44:47]
	v_mfma_f32_16x16x32_bf16 v[40:43], v[182:185], v[190:193], v[40:43]
	v_mfma_f32_16x16x32_bf16 v[28:31], v[170:173], v[202:205], v[28:31]
	v_mfma_f32_16x16x32_bf16 v[24:27], v[182:185], v[202:205], v[24:27]
	v_mfma_f32_16x16x32_bf16 v[12:15], v[170:173], v[210:213], v[12:15]
	v_mfma_f32_16x16x32_bf16 v[8:11], v[182:185], v[210:213], v[8:11]
	v_mfma_f32_16x16x32_bf16 v[4:7], v[170:173], v[218:221], v[4:7]
	v_mfma_f32_16x16x32_bf16 v[0:3], v[182:185], v[218:221], v[0:3]
	s_barrier
	s_setprio 0
	s_add_i32 s3, 0, 0x18000
	s_add_i32 s44, 0, 0x1c000
	v_add_u32_e32 v162, s3, v145
	v_add_u32_e32 v182, s44, v145
	ds_read_b128 v[150:153], v162
	ds_read_b128 v[154:157], v162 offset:1024
	ds_read_b128 v[158:161], v162 offset:2048
	ds_read_b128 v[162:165], v162 offset:3072
	ds_read_b128 v[166:169], v182
	ds_read_b128 v[170:173], v182 offset:1024
	ds_read_b128 v[174:177], v182 offset:2048
	ds_read_b128 v[182:185], v182 offset:3072
	s_add_u32 s36, s36, 0x80000
	s_addc_u32 s37, s37, 0
	s_mov_b32 m0, s52
	v_lshl_add_u64 v[226:227], s[36:37], 0, v[128:129]
	ds_read_b128 v[186:189], v149 offset:32768
	ds_read_b128 v[190:193], v149 offset:33792
	ds_read_b128 v[194:197], v149 offset:34816
	ds_read_b128 v[202:205], v149 offset:35840
	ds_read_b128 v[206:209], v149 offset:36864
	ds_read_b128 v[210:213], v149 offset:37888
	ds_read_b128 v[214:217], v149 offset:38912
	ds_read_b128 v[218:221], v149 offset:39936
	global_load_lds_dwordx4 v[226:227], off
	v_lshl_add_u64 v[226:227], s[36:37], 0, v[132:133]
	s_mov_b32 m0, s53
	s_nop 0
	global_load_lds_dwordx4 v[226:227], off
	s_waitcnt vmcnt(8)
	s_waitcnt lgkmcnt(0)
	s_setprio 1
	v_mfma_f32_16x16x32_bf16 v[124:127], v[150:153], v[186:189], v[124:127]
	v_mfma_f32_16x16x32_bf16 v[120:123], v[158:161], v[186:189], v[120:123]
	v_mfma_f32_16x16x32_bf16 v[116:119], v[150:153], v[194:197], v[116:119]
	v_mfma_f32_16x16x32_bf16 v[112:115], v[158:161], v[194:197], v[112:115]
	s_barrier
	v_mfma_f32_16x16x32_bf16 v[100:103], v[150:153], v[206:209], v[100:103]
	v_mfma_f32_16x16x32_bf16 v[96:99], v[158:161], v[206:209], v[96:99]
	v_mfma_f32_16x16x32_bf16 v[84:87], v[150:153], v[214:217], v[84:87]
	v_mfma_f32_16x16x32_bf16 v[80:83], v[158:161], v[214:217], v[80:83]
	v_mfma_f32_16x16x32_bf16 v[124:127], v[154:157], v[190:193], v[124:127]
	v_mfma_f32_16x16x32_bf16 v[120:123], v[162:165], v[190:193], v[120:123]
	v_mfma_f32_16x16x32_bf16 v[116:119], v[154:157], v[202:205], v[116:119]
	v_mfma_f32_16x16x32_bf16 v[112:115], v[162:165], v[202:205], v[112:115]
	v_mfma_f32_16x16x32_bf16 v[100:103], v[154:157], v[210:213], v[100:103]
	v_mfma_f32_16x16x32_bf16 v[96:99], v[162:165], v[210:213], v[96:99]
	v_mfma_f32_16x16x32_bf16 v[84:87], v[154:157], v[218:221], v[84:87]
	v_mfma_f32_16x16x32_bf16 v[80:83], v[162:165], v[218:221], v[80:83]
	v_mfma_f32_16x16x32_bf16 v[108:111], v[166:169], v[186:189], v[108:111]
	v_mfma_f32_16x16x32_bf16 v[104:107], v[174:177], v[186:189], v[104:107]
	v_mfma_f32_16x16x32_bf16 v[92:95], v[166:169], v[194:197], v[92:95]
	v_mfma_f32_16x16x32_bf16 v[88:91], v[174:177], v[194:197], v[88:91]
	v_mfma_f32_16x16x32_bf16 v[76:79], v[166:169], v[206:209], v[76:79]
	v_mfma_f32_16x16x32_bf16 v[72:75], v[174:177], v[206:209], v[72:75]
	v_mfma_f32_16x16x32_bf16 v[68:71], v[166:169], v[214:217], v[68:71]
	v_mfma_f32_16x16x32_bf16 v[64:67], v[174:177], v[214:217], v[64:67]
	v_mfma_f32_16x16x32_bf16 v[108:111], v[170:173], v[190:193], v[108:111]
	v_mfma_f32_16x16x32_bf16 v[104:107], v[182:185], v[190:193], v[104:107]
	v_mfma_f32_16x16x32_bf16 v[92:95], v[170:173], v[202:205], v[92:95]
	v_mfma_f32_16x16x32_bf16 v[88:91], v[182:185], v[202:205], v[88:91]
	v_mfma_f32_16x16x32_bf16 v[76:79], v[170:173], v[210:213], v[76:79]
	v_mfma_f32_16x16x32_bf16 v[72:75], v[182:185], v[210:213], v[72:75]
	v_mfma_f32_16x16x32_bf16 v[68:71], v[170:173], v[218:221], v[68:71]
	v_mfma_f32_16x16x32_bf16 v[64:67], v[182:185], v[218:221], v[64:67]
	s_barrier
; #define PG8_STAGE(bufoff, gbase, voff) do { _Pragma("unroll") for (int _i = 0; _i < 2; ++_i) \
;         __builtin_amdgcn_global_load_lds((const unsigned*)((const char*)(gbase) + (voff)[_i]), (PG8_LAS unsigned*)(lds + (bufoff) + ldsw + _i * 8192), 16, 0, 0); } while (0)
; #define PG8_LDA(dst, b, h) do { _Pragma("unroll") for (int m = 0; m < 4; ++m) _Pragma("unroll") for (int k = 0; k < 2; ++k) dst[m][k] = *(const PG8_LAS bf16x8*)(lds + PG8_SA(b, h) + aoff + m * 2048 + k * 1024); } while (0)
; #define PG8_MMA(ai, bj, At, Bt) do { __builtin_amdgcn_s_setprio(1); _Pragma("unroll") for (int m = 0; m < 4; ++m) _Pragma("unroll") for (int n = 0; n < 2; ++n) _Pragma("unroll") for (int k = 0; k < 2; ++k) \
;         acc[ai][bj][m][n] = __builtin_amdgcn_mfma_f32_16x16x32_bf16(Bt[n][k], At[m][k], acc[ai][bj][m][n], 0, 0, 0); __builtin_amdgcn_s_setprio(0); } while (0)
; #define PG8_WAIT_V(n) asm volatile("s_waitcnt vmcnt(" #n ")" ::: "memory")
; #define PG8_WAIT_L(n) asm volatile("s_waitcnt lgkmcnt(" #n ")" ::: "memory")
; #define PG8_BAR __builtin_amdgcn_s_barrier()
; #define PG8_SCHED __builtin_amdgcn_sched_barrier(0)
; template <class Epi, class Sched, bool ALIGN_EPI = false, bool SP2 = false>
; __device__ __forceinline__ void gemm_phase(PG8_LAS unsigned char* lds, const Gemm g, const Sched& S, const Epi& E) {
;     ...
;             PG8_WAIT_V(8); PG8_WAIT_L(0); PG8_BAR; PG8_MMA(0, 0, At, B0); PG8_MMA(0, 1, At, B1); PG8_BAR; PG8_SCHED;
;             PG8_LDA(At, 1, 1); PG8_STAGE(PG8_SB(1, 0), b3, voffB); PG8_STAGE(PG8_SB(1, 1), b3 + hstepB, voffB); PG8_STAGE(PG8_SA(1, 0), a3, voffA);
;             PG8_WAIT_V(8); PG8_WAIT_L(0); PG8_BAR; PG8_MMA(1, 0, At, B0); PG8_MMA(1, 1, At, B1); PG8_BAR; PG8_SCHED;
;     ...
;         if constexpr (ALIGN_EPI) { if (wr == 0) PG8_BAR; }
	s_setprio 0
	s_add_i32 s3, s3, s39
	v_lshl_add_u64 v[178:179], v[178:179], 0, s[10:11]
	s_mov_b32 m0, s3
	ds_read_b128 v[186:189], v149 offset:49152
	ds_read_b128 v[190:193], v149 offset:50176
	ds_read_b128 v[194:197], v149 offset:51200
	ds_read_b128 v[202:205], v149 offset:52224
	ds_read_b128 v[206:209], v149 offset:53248
	ds_read_b128 v[210:213], v149 offset:54272
	ds_read_b128 v[214:217], v149 offset:55296
	ds_read_b128 v[218:221], v149 offset:56320
	global_load_lds_dwordx4 v[178:179], off
	s_add_i32 m0, s3, 0x2000
	s_add_u32 s34, s34, 0x80080
	v_lshl_add_u64 v[178:179], v[198:199], 0, s[10:11]
	s_addc_u32 s35, s35, 0
	s_add_i32 s3, s44, s39
	global_load_lds_dwordx4 v[178:179], off
	v_lshl_add_u64 v[178:179], s[34:35], 0, v[130:131]
	s_mov_b32 m0, s3
	s_nop 0
	global_load_lds_dwordx4 v[178:179], off
	v_lshl_add_u64 v[178:179], s[34:35], 0, v[134:135]
	s_add_i32 m0, s3, 0x2000
	s_nop 0
	global_load_lds_dwordx4 v[178:179], off
	v_lshl_add_u64 v[178:179], v[222:223], 0, s[10:11]
	s_mov_b32 m0, s57
	s_nop 0
	global_load_lds_dwordx4 v[178:179], off
	v_lshl_add_u64 v[178:179], v[224:225], 0, s[10:11]
	s_mov_b32 m0, s62
	s_nop 0
	global_load_lds_dwordx4 v[178:179], off
	s_waitcnt vmcnt(8)
	s_waitcnt lgkmcnt(0)
	s_setprio 1
	v_mfma_f32_16x16x32_bf16 v[60:63], v[150:153], v[186:189], v[60:63]
	v_mfma_f32_16x16x32_bf16 v[56:59], v[158:161], v[186:189], v[56:59]
	v_mfma_f32_16x16x32_bf16 v[52:55], v[150:153], v[194:197], v[52:55]
	v_mfma_f32_16x16x32_bf16 v[48:51], v[158:161], v[194:197], v[48:51]
	s_barrier
	v_mfma_f32_16x16x32_bf16 v[36:39], v[150:153], v[206:209], v[36:39]
	v_mfma_f32_16x16x32_bf16 v[32:35], v[158:161], v[206:209], v[32:35]
	v_mfma_f32_16x16x32_bf16 v[20:23], v[150:153], v[214:217], v[20:23]
	v_mfma_f32_16x16x32_bf16 v[16:19], v[158:161], v[214:217], v[16:19]
	v_mfma_f32_16x16x32_bf16 v[60:63], v[154:157], v[190:193], v[60:63]
	v_mfma_f32_16x16x32_bf16 v[56:59], v[162:165], v[190:193], v[56:59]
	v_mfma_f32_16x16x32_bf16 v[52:55], v[154:157], v[202:205], v[52:55]
	v_mfma_f32_16x16x32_bf16 v[48:51], v[162:165], v[202:205], v[48:51]
	v_mfma_f32_16x16x32_bf16 v[36:39], v[154:157], v[210:213], v[36:39]
	v_mfma_f32_16x16x32_bf16 v[32:35], v[162:165], v[210:213], v[32:35]
	v_mfma_f32_16x16x32_bf16 v[20:23], v[154:157], v[218:221], v[20:23]
	v_mfma_f32_16x16x32_bf16 v[16:19], v[162:165], v[218:221], v[16:19]
	v_mfma_f32_16x16x32_bf16 v[44:47], v[166:169], v[186:189], v[44:47]
	v_mfma_f32_16x16x32_bf16 v[40:43], v[174:177], v[186:189], v[40:43]
	v_mfma_f32_16x16x32_bf16 v[28:31], v[166:169], v[194:197], v[28:31]
	v_mfma_f32_16x16x32_bf16 v[24:27], v[174:177], v[194:197], v[24:27]
	v_mfma_f32_16x16x32_bf16 v[12:15], v[166:169], v[206:209], v[12:15]
	v_mfma_f32_16x16x32_bf16 v[8:11], v[174:177], v[206:209], v[8:11]
	v_mfma_f32_16x16x32_bf16 v[4:7], v[166:169], v[214:217], v[4:7]
	v_mfma_f32_16x16x32_bf16 v[0:3], v[174:177], v[214:217], v[0:3]
	v_mfma_f32_16x16x32_bf16 v[44:47], v[170:173], v[190:193], v[44:47]
	v_mfma_f32_16x16x32_bf16 v[40:43], v[182:185], v[190:193], v[40:43]
	v_mfma_f32_16x16x32_bf16 v[28:31], v[170:173], v[202:205], v[28:31]
	v_mfma_f32_16x16x32_bf16 v[24:27], v[182:185], v[202:205], v[24:27]
	v_mfma_f32_16x16x32_bf16 v[12:15], v[170:173], v[210:213], v[12:15]
	v_mfma_f32_16x16x32_bf16 v[8:11], v[182:185], v[210:213], v[8:11]
	v_mfma_f32_16x16x32_bf16 v[4:7], v[170:173], v[218:221], v[4:7]
	v_mfma_f32_16x16x32_bf16 v[0:3], v[182:185], v[218:221], v[0:3]
	s_barrier
	s_setprio 0
	s_add_i32 s88, s88, 2
	s_add_u32 s30, s30, 0x100
	s_addc_u32 s31, s31, 0
	s_add_u32 s86, s86, 0x100
	s_addc_u32 s87, s87, 0
	s_cmp_gt_u32 s88, 29
	s_cbranch_scc0 .LBB0_540
	s_and_b64 vcc, exec, s[12:13]
	s_cbranch_vccz .LBB0_543
	s_barrier

; #define PG8_STAGE(bufoff, gbase, voff) do { _Pragma("unroll") for (int _i = 0; _i < 2; ++_i) \
;         __builtin_amdgcn_global_load_lds((const unsigned*)((const char*)(gbase) + (voff)[_i]), (PG8_LAS unsigned*)(lds + (bufoff) + ldsw + _i * 8192), 16, 0, 0); } while (0)
; #define PG8_LDA(dst, b, h) do { _Pragma("unroll") for (int m = 0; m < 4; ++m) _Pragma("unroll") for (int k = 0; k < 2; ++k) dst[m][k] = *(const PG8_LAS bf16x8*)(lds + PG8_SA(b, h) + aoff + m * 2048 + k * 1024); } while (0)
; #define PG8_LDB(dst, b, h) do { _Pragma("unroll") for (int n = 0; n < 2; ++n) _Pragma("unroll") for (int k = 0; k < 2; ++k) dst[n][k] = *(const PG8_LAS bf16x8*)(lds + PG8_SB(b, h) + boff + n * 2048 + k * 1024); } while (0)
; #define PG8_MMA(ai, bj, At, Bt) do { __builtin_amdgcn_s_setprio(1); _Pragma("unroll") for (int m = 0; m < 4; ++m) _Pragma("unroll") for (int n = 0; n < 2; ++n) _Pragma("unroll") for (int k = 0; k < 2; ++k) \
;         acc[ai][bj][m][n] = __builtin_amdgcn_mfma_f32_16x16x32_bf16(Bt[n][k], At[m][k], acc[ai][bj][m][n], 0, 0, 0); __builtin_amdgcn_s_setprio(0); } while (0)
; #define PG8_WAIT_V(n) asm volatile("s_waitcnt vmcnt(" #n ")" ::: "memory")
; #define PG8_BAR __builtin_amdgcn_s_barrier()
; template <class Epi, class Sched, bool ALIGN_EPI = false, bool SP2 = false>
; __device__ __forceinline__ void gemm_phase(PG8_LAS unsigned char* lds, const Gemm g, const Sched& S, const Epi& E) {
;     ...
;         for (int t = 0; t < nt; t += 2) {
;             const bool last = (t == nt - 2);
;             const char* a1 = cA + (size_t)(t + 1) * kstep;
;             const char* a2 = last ? nA : cA + (size_t)(t + 2) * kstep; const char* b2 = last ? nB : cB + (size_t)(t + 2) * kstep;
;             const char* a3 = a2 + kstep; const char* b3 = b2 + kstep;
;             if (last && has_next) S.a_ready(nxt);
;             if constexpr (SP2) {
;             PG8_LDB(B0, 0, 0); PG8_LDB(B1, 0, 1); PG8_SCHED; PG8_LDA(At, 0, 0); PG8_STAGE(PG8_SA(1, 1), a1 + hstepA, voffA);
;             PG8_WAIT_V(8); PG8_WAIT_L(0); PG8_BAR; PG8_MMA(0, 0, At, B0); PG8_MMA(0, 1, At, B1); PG8_BAR; PG8_SCHED;
;             PG8_LDA(At, 0, 1); PG8_STAGE(PG8_SB(0, 0), b2, voffB); PG8_STAGE(PG8_SB(0, 1), b2 + hstepB, voffB); PG8_STAGE(PG8_SA(0, 0), a2, voffA);
;             PG8_WAIT_V(8); PG8_WAIT_L(0); PG8_BAR; PG8_MMA(1, 0, At, B0); PG8_MMA(1, 1, At, B1); PG8_BAR; PG8_SCHED;
.LBB0_665:
	ds_read_b128 v[144:147], v155
	ds_read_b128 v[162:165], v155 offset:1024
	ds_read_b128 v[166:169], v155 offset:2048
	ds_read_b128 v[170:173], v155 offset:3072
	ds_read_b128 v[174:177], v159
	ds_read_b128 v[182:185], v159 offset:1024
	ds_read_b128 v[186:189], v159 offset:2048
	ds_read_b128 v[190:193], v159 offset:3072
	s_add_u32 s3, s24, 0xfff80080
	s_addc_u32 s26, s25, -1
	s_cmp_eq_u32 s62, 28
	s_cselect_b32 s29, s15, s26
	s_cselect_b32 s28, s58, s3
	s_cselect_b32 s27, s17, s61
	s_cselect_b32 s26, s59, s60
	v_lshl_add_u64 v[156:157], s[24:25], 0, v[136:137]
	s_add_i32 m0, s23, 0xc000
	ds_read_b128 v[194:197], v161
	ds_read_b128 v[202:205], v161 offset:1024
	ds_read_b128 v[206:209], v161 offset:2048
	ds_read_b128 v[210:213], v161 offset:3072
	ds_read_b128 v[214:217], v161 offset:4096
	ds_read_b128 v[218:221], v161 offset:5120
	ds_read_b128 v[222:225], v161 offset:6144
	ds_read_b128 v[226:229], v161 offset:7168
	global_load_lds_dwordx4 v[156:157], off
	v_lshl_add_u64 v[156:157], s[24:25], 0, v[138:139]
	s_add_i32 m0, s23, 0xe000
	s_nop 0
	global_load_lds_dwordx4 v[156:157], off
	s_waitcnt vmcnt(8)
	s_waitcnt lgkmcnt(0)
	s_setprio 1
	v_mfma_f32_16x16x32_bf16 v[124:127], v[144:147], v[194:197], v[124:127]
	v_mfma_f32_16x16x32_bf16 v[120:123], v[166:169], v[194:197], v[120:123]
	v_mfma_f32_16x16x32_bf16 v[108:111], v[144:147], v[206:209], v[108:111]
	v_mfma_f32_16x16x32_bf16 v[104:107], v[166:169], v[206:209], v[104:107]
	s_barrier
	v_mfma_f32_16x16x32_bf16 v[92:95], v[144:147], v[214:217], v[92:95]
	v_mfma_f32_16x16x32_bf16 v[88:91], v[166:169], v[214:217], v[88:91]
	v_mfma_f32_16x16x32_bf16 v[76:79], v[144:147], v[222:225], v[76:79]
	v_mfma_f32_16x16x32_bf16 v[72:75], v[166:169], v[222:225], v[72:75]
	v_mfma_f32_16x16x32_bf16 v[124:127], v[162:165], v[202:205], v[124:127]
	v_mfma_f32_16x16x32_bf16 v[120:123], v[170:173], v[202:205], v[120:123]
	v_mfma_f32_16x16x32_bf16 v[108:111], v[162:165], v[210:213], v[108:111]
	v_mfma_f32_16x16x32_bf16 v[104:107], v[170:173], v[210:213], v[104:107]
	v_mfma_f32_16x16x32_bf16 v[92:95], v[162:165], v[218:221], v[92:95]
	v_mfma_f32_16x16x32_bf16 v[88:91], v[170:173], v[218:221], v[88:91]
	v_mfma_f32_16x16x32_bf16 v[76:79], v[162:165], v[226:229], v[76:79]
	v_mfma_f32_16x16x32_bf16 v[72:75], v[170:173], v[226:229], v[72:75]
	v_mfma_f32_16x16x32_bf16 v[116:119], v[174:177], v[194:197], v[116:119]
	v_mfma_f32_16x16x32_bf16 v[112:115], v[186:189], v[194:197], v[112:115]
	v_mfma_f32_16x16x32_bf16 v[100:103], v[174:177], v[206:209], v[100:103]
	v_mfma_f32_16x16x32_bf16 v[96:99], v[186:189], v[206:209], v[96:99]
	v_mfma_f32_16x16x32_bf16 v[84:87], v[174:177], v[214:217], v[84:87]
	v_mfma_f32_16x16x32_bf16 v[80:83], v[186:189], v[214:217], v[80:83]
	v_mfma_f32_16x16x32_bf16 v[68:71], v[174:177], v[222:225], v[68:71]
	v_mfma_f32_16x16x32_bf16 v[64:67], v[186:189], v[222:225], v[64:67]
	v_mfma_f32_16x16x32_bf16 v[116:119], v[182:185], v[202:205], v[116:119]
	v_mfma_f32_16x16x32_bf16 v[112:115], v[190:193], v[202:205], v[112:115]
	v_mfma_f32_16x16x32_bf16 v[100:103], v[182:185], v[210:213], v[100:103]
	v_mfma_f32_16x16x32_bf16 v[96:99], v[190:193], v[210:213], v[96:99]
	v_mfma_f32_16x16x32_bf16 v[84:87], v[182:185], v[218:221], v[84:87]
	v_mfma_f32_16x16x32_bf16 v[80:83], v[190:193], v[218:221], v[80:83]
	v_mfma_f32_16x16x32_bf16 v[68:71], v[182:185], v[226:229], v[68:71]
	v_mfma_f32_16x16x32_bf16 v[64:67], v[190:193], v[226:229], v[64:67]
	s_barrier
	s_setprio 0
	s_add_i32 s3, s54, s30
	v_lshl_add_u64 v[156:157], s[26:27], 0, v[132:133]
	s_mov_b32 m0, s3
	ds_read_b128 v[194:197], v161 offset:16384
	ds_read_b128 v[202:205], v161 offset:17408
	ds_read_b128 v[206:209], v161 offset:18432
	ds_read_b128 v[210:213], v161 offset:19456
	ds_read_b128 v[214:217], v161 offset:20480
	ds_read_b128 v[218:221], v161 offset:21504
	ds_read_b128 v[222:225], v161 offset:22528
	ds_read_b128 v[226:229], v161 offset:23552
	global_load_lds_dwordx4 v[156:157], off
	s_add_i32 m0, s3, 0x2000
	s_add_u32 s44, s26, 0x80000
	v_lshl_add_u64 v[178:179], s[26:27], 0, v[128:129]
	s_addc_u32 s45, s27, 0
	s_add_i32 s3, s55, s30
	global_load_lds_dwordx4 v[178:179], off
	v_lshl_add_u64 v[198:199], s[44:45], 0, v[132:133]
	s_mov_b32 m0, s3
	v_lshl_add_u64 v[230:231], s[28:29], 0, v[130:131]
	global_load_lds_dwordx4 v[198:199], off
	v_lshl_add_u64 v[198:199], s[44:45], 0, v[128:129]
	s_add_i32 m0, s3, 0x2000
	s_nop 0
	global_load_lds_dwordx4 v[198:199], off
	v_lshl_add_u64 v[198:199], s[28:29], 0, v[134:135]
	s_mov_b32 m0, s23
	s_nop 0
	global_load_lds_dwordx4 v[198:199], off
	s_mov_b32 m0, s35
	s_nop 0
	global_load_lds_dwordx4 v[230:231], off
	s_waitcnt vmcnt(8)
	s_waitcnt lgkmcnt(0)
	s_setprio 1
	v_mfma_f32_16x16x32_bf16 v[60:63], v[144:147], v[194:197], v[60:63]
	v_mfma_f32_16x16x32_bf16 v[56:59], v[166:169], v[194:197], v[56:59]
	v_mfma_f32_16x16x32_bf16 v[44:47], v[144:147], v[206:209], v[44:47]
	v_mfma_f32_16x16x32_bf16 v[40:43], v[166:169], v[206:209], v[40:43]
	s_barrier
; #define PG8_STAGE(bufoff, gbase, voff) do { _Pragma("unroll") for (int _i = 0; _i < 2; ++_i) \
;         __builtin_amdgcn_global_load_lds((const unsigned*)((const char*)(gbase) + (voff)[_i]), (PG8_LAS unsigned*)(lds + (bufoff) + ldsw + _i * 8192), 16, 0, 0); } while (0)
; #define PG8_LDA(dst, b, h) do { _Pragma("unroll") for (int m = 0; m < 4; ++m) _Pragma("unroll") for (int k = 0; k < 2; ++k) dst[m][k] = *(const PG8_LAS bf16x8*)(lds + PG8_SA(b, h) + aoff + m * 2048 + k * 1024); } while (0)
; #define PG8_LDB(dst, b, h) do { _Pragma("unroll") for (int n = 0; n < 2; ++n) _Pragma("unroll") for (int k = 0; k < 2; ++k) dst[n][k] = *(const PG8_LAS bf16x8*)(lds + PG8_SB(b, h) + boff + n * 2048 + k * 1024); } while (0)
; #define PG8_MMA(ai, bj, At, Bt) do { __builtin_amdgcn_s_setprio(1); _Pragma("unroll") for (int m = 0; m < 4; ++m) _Pragma("unroll") for (int n = 0; n < 2; ++n) _Pragma("unroll") for (int k = 0; k < 2; ++k) \
;         acc[ai][bj][m][n] = __builtin_amdgcn_mfma_f32_16x16x32_bf16(Bt[n][k], At[m][k], acc[ai][bj][m][n], 0, 0, 0); __builtin_amdgcn_s_setprio(0); } while (0)
; #define PG8_WAIT_V(n) asm volatile("s_waitcnt vmcnt(" #n ")" ::: "memory")
; #define PG8_WAIT_L(n) asm volatile("s_waitcnt lgkmcnt(" #n ")" ::: "memory")
; #define PG8_BAR __builtin_amdgcn_s_barrier()
; #define PG8_SCHED __builtin_amdgcn_sched_barrier(0)
; template <class Epi, class Sched, bool ALIGN_EPI = false, bool SP2 = false>
; __device__ __forceinline__ void gemm_phase(PG8_LAS unsigned char* lds, const Gemm g, const Sched& S, const Epi& E) {
;     ...
;             PG8_WAIT_V(8); PG8_WAIT_L(0); PG8_BAR; PG8_MMA(1, 0, At, B0); PG8_MMA(1, 1, At, B1); PG8_BAR; PG8_SCHED;
;             PG8_LDB(B0, 1, 0); PG8_LDB(B1, 1, 1); PG8_SCHED; PG8_LDA(At, 1, 0); PG8_STAGE(PG8_SA(0, 1), a2 + hstepA, voffA);
;             PG8_WAIT_V(8); PG8_WAIT_L(0); PG8_BAR; PG8_MMA(0, 0, At, B0); PG8_MMA(0, 1, At, B1); PG8_BAR; PG8_SCHED;
	v_mfma_f32_16x16x32_bf16 v[28:31], v[144:147], v[214:217], v[28:31]
	v_mfma_f32_16x16x32_bf16 v[24:27], v[166:169], v[214:217], v[24:27]
	v_mfma_f32_16x16x32_bf16 v[12:15], v[144:147], v[222:225], v[12:15]
	v_mfma_f32_16x16x32_bf16 v[8:11], v[166:169], v[222:225], v[8:11]
	v_mfma_f32_16x16x32_bf16 v[60:63], v[162:165], v[202:205], v[60:63]
	v_mfma_f32_16x16x32_bf16 v[56:59], v[170:173], v[202:205], v[56:59]
	v_mfma_f32_16x16x32_bf16 v[44:47], v[162:165], v[210:213], v[44:47]
	v_mfma_f32_16x16x32_bf16 v[40:43], v[170:173], v[210:213], v[40:43]
	v_mfma_f32_16x16x32_bf16 v[28:31], v[162:165], v[218:221], v[28:31]
	v_mfma_f32_16x16x32_bf16 v[24:27], v[170:173], v[218:221], v[24:27]
	v_mfma_f32_16x16x32_bf16 v[12:15], v[162:165], v[226:229], v[12:15]
	v_mfma_f32_16x16x32_bf16 v[8:11], v[170:173], v[226:229], v[8:11]
	v_mfma_f32_16x16x32_bf16 v[52:55], v[174:177], v[194:197], v[52:55]
	v_mfma_f32_16x16x32_bf16 v[48:51], v[186:189], v[194:197], v[48:51]
	v_mfma_f32_16x16x32_bf16 v[36:39], v[174:177], v[206:209], v[36:39]
	v_mfma_f32_16x16x32_bf16 v[32:35], v[186:189], v[206:209], v[32:35]
	v_mfma_f32_16x16x32_bf16 v[20:23], v[174:177], v[214:217], v[20:23]
	v_mfma_f32_16x16x32_bf16 v[16:19], v[186:189], v[214:217], v[16:19]
	v_mfma_f32_16x16x32_bf16 v[4:7], v[174:177], v[222:225], v[4:7]
	v_mfma_f32_16x16x32_bf16 v[0:3], v[186:189], v[222:225], v[0:3]
	v_mfma_f32_16x16x32_bf16 v[52:55], v[182:185], v[202:205], v[52:55]
	v_mfma_f32_16x16x32_bf16 v[48:51], v[190:193], v[202:205], v[48:51]
	v_mfma_f32_16x16x32_bf16 v[36:39], v[182:185], v[210:213], v[36:39]
	v_mfma_f32_16x16x32_bf16 v[32:35], v[190:193], v[210:213], v[32:35]
	v_mfma_f32_16x16x32_bf16 v[20:23], v[182:185], v[218:221], v[20:23]
	v_mfma_f32_16x16x32_bf16 v[16:19], v[190:193], v[218:221], v[16:19]
	v_mfma_f32_16x16x32_bf16 v[4:7], v[182:185], v[226:229], v[4:7]
	v_mfma_f32_16x16x32_bf16 v[0:3], v[190:193], v[226:229], v[0:3]
	s_barrier
	s_setprio 0
	s_add_i32 s3, 0, 0x18000
	v_add_u32_e32 v148, s3, v151
	s_add_i32 s44, 0, 0x1c000
	ds_read_b128 v[144:147], v148
	ds_read_b128 v[162:165], v148 offset:1024
	ds_read_b128 v[166:169], v148 offset:2048
	ds_read_b128 v[170:173], v148 offset:3072
	v_add_u32_e32 v148, s44, v151
	ds_read_b128 v[174:177], v148
	ds_read_b128 v[182:185], v148 offset:1024
	ds_read_b128 v[186:189], v148 offset:2048
	ds_read_b128 v[190:193], v148 offset:3072
	s_add_u32 s28, s28, 0x80000
	s_addc_u32 s29, s29, 0
	s_mov_b32 m0, s36
	v_lshl_add_u64 v[232:233], s[28:29], 0, v[134:135]
	ds_read_b128 v[194:197], v161 offset:32768
	ds_read_b128 v[202:205], v161 offset:33792
	ds_read_b128 v[206:209], v161 offset:34816
	ds_read_b128 v[210:213], v161 offset:35840
	ds_read_b128 v[214:217], v161 offset:36864
	ds_read_b128 v[218:221], v161 offset:37888
	ds_read_b128 v[222:225], v161 offset:38912
	ds_read_b128 v[226:229], v161 offset:39936
	global_load_lds_dwordx4 v[232:233], off
	v_lshl_add_u64 v[232:233], s[28:29], 0, v[130:131]
	s_mov_b32 m0, s37
	s_nop 0
	global_load_lds_dwordx4 v[232:233], off
	s_waitcnt vmcnt(8)
	s_waitcnt lgkmcnt(0)
	s_setprio 1
	v_mfma_f32_16x16x32_bf16 v[124:127], v[144:147], v[194:197], v[124:127]
	v_mfma_f32_16x16x32_bf16 v[120:123], v[166:169], v[194:197], v[120:123]
	v_mfma_f32_16x16x32_bf16 v[108:111], v[144:147], v[206:209], v[108:111]
	v_mfma_f32_16x16x32_bf16 v[104:107], v[166:169], v[206:209], v[104:107]
	s_barrier
	v_mfma_f32_16x16x32_bf16 v[92:95], v[144:147], v[214:217], v[92:95]
	v_mfma_f32_16x16x32_bf16 v[88:91], v[166:169], v[214:217], v[88:91]
	v_mfma_f32_16x16x32_bf16 v[76:79], v[144:147], v[222:225], v[76:79]
	v_mfma_f32_16x16x32_bf16 v[72:75], v[166:169], v[222:225], v[72:75]
	v_mfma_f32_16x16x32_bf16 v[124:127], v[162:165], v[202:205], v[124:127]
	v_mfma_f32_16x16x32_bf16 v[120:123], v[170:173], v[202:205], v[120:123]
	v_mfma_f32_16x16x32_bf16 v[108:111], v[162:165], v[210:213], v[108:111]
	v_mfma_f32_16x16x32_bf16 v[104:107], v[170:173], v[210:213], v[104:107]
	v_mfma_f32_16x16x32_bf16 v[92:95], v[162:165], v[218:221], v[92:95]
	v_mfma_f32_16x16x32_bf16 v[88:91], v[170:173], v[218:221], v[88:91]
	v_mfma_f32_16x16x32_bf16 v[76:79], v[162:165], v[226:229], v[76:79]
	v_mfma_f32_16x16x32_bf16 v[72:75], v[170:173], v[226:229], v[72:75]
	v_mfma_f32_16x16x32_bf16 v[116:119], v[174:177], v[194:197], v[116:119]
	v_mfma_f32_16x16x32_bf16 v[112:115], v[186:189], v[194:197], v[112:115]
	v_mfma_f32_16x16x32_bf16 v[100:103], v[174:177], v[206:209], v[100:103]
	v_mfma_f32_16x16x32_bf16 v[96:99], v[186:189], v[206:209], v[96:99]
	v_mfma_f32_16x16x32_bf16 v[84:87], v[174:177], v[214:217], v[84:87]
	v_mfma_f32_16x16x32_bf16 v[80:83], v[186:189], v[214:217], v[80:83]
	v_mfma_f32_16x16x32_bf16 v[68:71], v[174:177], v[222:225], v[68:71]
	v_mfma_f32_16x16x32_bf16 v[64:67], v[186:189], v[222:225], v[64:67]
	v_mfma_f32_16x16x32_bf16 v[116:119], v[182:185], v[202:205], v[116:119]
	v_mfma_f32_16x16x32_bf16 v[112:115], v[190:193], v[202:205], v[112:115]
	v_mfma_f32_16x16x32_bf16 v[100:103], v[182:185], v[210:213], v[100:103]
	v_mfma_f32_16x16x32_bf16 v[96:99], v[190:193], v[210:213], v[96:99]
	v_mfma_f32_16x16x32_bf16 v[84:87], v[182:185], v[218:221], v[84:87]
	v_mfma_f32_16x16x32_bf16 v[80:83], v[190:193], v[218:221], v[80:83]
	v_mfma_f32_16x16x32_bf16 v[68:71], v[182:185], v[226:229], v[68:71]
	v_mfma_f32_16x16x32_bf16 v[64:67], v[190:193], v[226:229], v[64:67]
	s_barrier
; #define PG8_STAGE(bufoff, gbase, voff) do { _Pragma("unroll") for (int _i = 0; _i < 2; ++_i) \
;         __builtin_amdgcn_global_load_lds((const unsigned*)((const char*)(gbase) + (voff)[_i]), (PG8_LAS unsigned*)(lds + (bufoff) + ldsw + _i * 8192), 16, 0, 0); } while (0)
; #define PG8_LDA(dst, b, h) do { _Pragma("unroll") for (int m = 0; m < 4; ++m) _Pragma("unroll") for (int k = 0; k < 2; ++k) dst[m][k] = *(const PG8_LAS bf16x8*)(lds + PG8_SA(b, h) + aoff + m * 2048 + k * 1024); } while (0)
; #define PG8_MMA(ai, bj, At, Bt) do { __builtin_amdgcn_s_setprio(1); _Pragma("unroll") for (int m = 0; m < 4; ++m) _Pragma("unroll") for (int n = 0; n < 2; ++n) _Pragma("unroll") for (int k = 0; k < 2; ++k) \
;         acc[ai][bj][m][n] = __builtin_amdgcn_mfma_f32_16x16x32_bf16(Bt[n][k], At[m][k], acc[ai][bj][m][n], 0, 0, 0); __builtin_amdgcn_s_setprio(0); } while (0)
; #define PG8_WAIT_V(n) asm volatile("s_waitcnt vmcnt(" #n ")" ::: "memory")
; #define PG8_WAIT_L(n) asm volatile("s_waitcnt lgkmcnt(" #n ")" ::: "memory")
; #define PG8_BAR __builtin_amdgcn_s_barrier()
; #define PG8_SCHED __builtin_amdgcn_sched_barrier(0)
; template <class Epi, class Sched, bool ALIGN_EPI = false, bool SP2 = false>
; __device__ __forceinline__ void gemm_phase(PG8_LAS unsigned char* lds, const Gemm g, const Sched& S, const Epi& E) {
;     ...
;             PG8_WAIT_V(8); PG8_WAIT_L(0); PG8_BAR; PG8_MMA(0, 0, At, B0); PG8_MMA(0, 1, At, B1); PG8_BAR; PG8_SCHED;
;             PG8_LDA(At, 1, 1); PG8_STAGE(PG8_SB(1, 0), b3, voffB); PG8_STAGE(PG8_SB(1, 1), b3 + hstepB, voffB); PG8_STAGE(PG8_SA(1, 0), a3, voffA);
;             PG8_WAIT_V(8); PG8_WAIT_L(0); PG8_BAR; PG8_MMA(1, 0, At, B0); PG8_MMA(1, 1, At, B1); PG8_BAR; PG8_SCHED;
;     ...
;         if constexpr (ALIGN_EPI) { if (wr == 0) PG8_BAR; }
	s_setprio 0
	s_add_i32 s3, s3, s30
	v_lshl_add_u64 v[156:157], v[156:157], 0, s[10:11]
	s_mov_b32 m0, s3
	ds_read_b128 v[194:197], v161 offset:49152
	ds_read_b128 v[202:205], v161 offset:50176
	ds_read_b128 v[206:209], v161 offset:51200
	ds_read_b128 v[210:213], v161 offset:52224
	ds_read_b128 v[214:217], v161 offset:53248
	ds_read_b128 v[218:221], v161 offset:54272
	ds_read_b128 v[222:225], v161 offset:55296
	ds_read_b128 v[226:229], v161 offset:56320
	global_load_lds_dwordx4 v[156:157], off
	s_add_i32 m0, s3, 0x2000
	s_add_u32 s26, s26, 0x80080
	v_lshl_add_u64 v[156:157], v[178:179], 0, s[10:11]
	s_addc_u32 s27, s27, 0
	s_add_i32 s3, s44, s30
	global_load_lds_dwordx4 v[156:157], off
	v_lshl_add_u64 v[156:157], s[26:27], 0, v[132:133]
	s_mov_b32 m0, s3
	s_nop 0
	global_load_lds_dwordx4 v[156:157], off
	v_lshl_add_u64 v[156:157], s[26:27], 0, v[128:129]
	s_add_i32 m0, s3, 0x2000
	s_nop 0
	global_load_lds_dwordx4 v[156:157], off
	v_lshl_add_u64 v[156:157], v[198:199], 0, s[10:11]
	s_mov_b32 m0, s39
	s_nop 0
	global_load_lds_dwordx4 v[156:157], off
	v_lshl_add_u64 v[156:157], v[230:231], 0, s[10:11]
	s_mov_b32 m0, s43
	s_nop 0
	global_load_lds_dwordx4 v[156:157], off
	s_waitcnt vmcnt(8)
	s_waitcnt lgkmcnt(0)
	s_setprio 1
	v_mfma_f32_16x16x32_bf16 v[60:63], v[144:147], v[194:197], v[60:63]
	v_mfma_f32_16x16x32_bf16 v[56:59], v[166:169], v[194:197], v[56:59]
	v_mfma_f32_16x16x32_bf16 v[44:47], v[144:147], v[206:209], v[44:47]
	v_mfma_f32_16x16x32_bf16 v[40:43], v[166:169], v[206:209], v[40:43]
	s_barrier
	v_mfma_f32_16x16x32_bf16 v[28:31], v[144:147], v[214:217], v[28:31]
	v_mfma_f32_16x16x32_bf16 v[24:27], v[166:169], v[214:217], v[24:27]
	v_mfma_f32_16x16x32_bf16 v[12:15], v[144:147], v[222:225], v[12:15]
	v_mfma_f32_16x16x32_bf16 v[8:11], v[166:169], v[222:225], v[8:11]
	v_mfma_f32_16x16x32_bf16 v[60:63], v[162:165], v[202:205], v[60:63]
	v_mfma_f32_16x16x32_bf16 v[56:59], v[170:173], v[202:205], v[56:59]
	v_mfma_f32_16x16x32_bf16 v[44:47], v[162:165], v[210:213], v[44:47]
	v_mfma_f32_16x16x32_bf16 v[40:43], v[170:173], v[210:213], v[40:43]
	v_mfma_f32_16x16x32_bf16 v[28:31], v[162:165], v[218:221], v[28:31]
	v_mfma_f32_16x16x32_bf16 v[24:27], v[170:173], v[218:221], v[24:27]
	v_mfma_f32_16x16x32_bf16 v[12:15], v[162:165], v[226:229], v[12:15]
	v_mfma_f32_16x16x32_bf16 v[8:11], v[170:173], v[226:229], v[8:11]
	v_mfma_f32_16x16x32_bf16 v[52:55], v[174:177], v[194:197], v[52:55]
	v_mfma_f32_16x16x32_bf16 v[48:51], v[186:189], v[194:197], v[48:51]
	v_mfma_f32_16x16x32_bf16 v[36:39], v[174:177], v[206:209], v[36:39]
	v_mfma_f32_16x16x32_bf16 v[32:35], v[186:189], v[206:209], v[32:35]
	v_mfma_f32_16x16x32_bf16 v[20:23], v[174:177], v[214:217], v[20:23]
	v_mfma_f32_16x16x32_bf16 v[16:19], v[186:189], v[214:217], v[16:19]
	v_mfma_f32_16x16x32_bf16 v[4:7], v[174:177], v[222:225], v[4:7]
	v_mfma_f32_16x16x32_bf16 v[0:3], v[186:189], v[222:225], v[0:3]
	v_mfma_f32_16x16x32_bf16 v[52:55], v[182:185], v[202:205], v[52:55]
	v_mfma_f32_16x16x32_bf16 v[48:51], v[190:193], v[202:205], v[48:51]
	v_mfma_f32_16x16x32_bf16 v[36:39], v[182:185], v[210:213], v[36:39]
	v_mfma_f32_16x16x32_bf16 v[32:35], v[190:193], v[210:213], v[32:35]
	v_mfma_f32_16x16x32_bf16 v[20:23], v[182:185], v[218:221], v[20:23]
	v_mfma_f32_16x16x32_bf16 v[16:19], v[190:193], v[218:221], v[16:19]
	v_mfma_f32_16x16x32_bf16 v[4:7], v[182:185], v[226:229], v[4:7]
	v_mfma_f32_16x16x32_bf16 v[0:3], v[190:193], v[226:229], v[0:3]
	s_barrier
	s_setprio 0
	s_add_i32 s62, s62, 2
	s_add_u32 s24, s24, 0x100
	s_addc_u32 s25, s25, 0
	s_add_u32 s60, s60, 0x100
	s_addc_u32 s61, s61, 0
	s_cmp_gt_u32 s62, 29
	s_cbranch_scc0 .LBB0_665
	s_and_b64 vcc, exec, s[12:13]
	s_cbranch_vccz .LBB0_668
	s_barrier

; #define PG8_STAGE(bufoff, gbase, voff) do { _Pragma("unroll") for (int _i = 0; _i < 2; ++_i) \
;         __builtin_amdgcn_global_load_lds((const unsigned*)((const char*)(gbase) + (voff)[_i]), (PG8_LAS unsigned*)(lds + (bufoff) + ldsw + _i * 8192), 16, 0, 0); } while (0)
; #define PG8_LDA(dst, b, h) do { _Pragma("unroll") for (int m = 0; m < 4; ++m) _Pragma("unroll") for (int k = 0; k < 2; ++k) dst[m][k] = *(const PG8_LAS bf16x8*)(lds + PG8_SA(b, h) + aoff + m * 2048 + k * 1024); } while (0)
; #define PG8_LDB(dst, b, h) do { _Pragma("unroll") for (int n = 0; n < 2; ++n) _Pragma("unroll") for (int k = 0; k < 2; ++k) dst[n][k] = *(const PG8_LAS bf16x8*)(lds + PG8_SB(b, h) + boff + n * 2048 + k * 1024); } while (0)
; #define PG8_MMA(ai, bj, At, Bt) do { __builtin_amdgcn_s_setprio(1); _Pragma("unroll") for (int m = 0; m < 4; ++m) _Pragma("unroll") for (int n = 0; n < 2; ++n) _Pragma("unroll") for (int k = 0; k < 2; ++k) \
;         acc[ai][bj][m][n] = __builtin_amdgcn_mfma_f32_16x16x32_bf16(Bt[n][k], At[m][k], acc[ai][bj][m][n], 0, 0, 0); __builtin_amdgcn_s_setprio(0); } while (0)
; #define PG8_WAIT_V(n) asm volatile("s_waitcnt vmcnt(" #n ")" ::: "memory")
; #define PG8_BAR __builtin_amdgcn_s_barrier()
; template <class Epi, class Sched, bool ALIGN_EPI = false, bool SP2 = false>
; __device__ __forceinline__ void gemm_phase(PG8_LAS unsigned char* lds, const Gemm g, const Sched& S, const Epi& E) {
;     ...
;         for (int t = 0; t < nt; t += 2) {
;             const bool last = (t == nt - 2);
;             const char* a1 = cA + (size_t)(t + 1) * kstep;
;             const char* a2 = last ? nA : cA + (size_t)(t + 2) * kstep; const char* b2 = last ? nB : cB + (size_t)(t + 2) * kstep;
;             const char* a3 = a2 + kstep; const char* b3 = b2 + kstep;
;             if (last && has_next) S.a_ready(nxt);
;             if constexpr (SP2) {
;             PG8_LDB(B0, 0, 0); PG8_LDB(B1, 0, 1); PG8_SCHED; PG8_LDA(At, 0, 0); PG8_STAGE(PG8_SA(1, 1), a1 + hstepA, voffA);
;             PG8_WAIT_V(8); PG8_WAIT_L(0); PG8_BAR; PG8_MMA(0, 0, At, B0); PG8_MMA(0, 1, At, B1); PG8_BAR; PG8_SCHED;
;             PG8_LDA(At, 0, 1); PG8_STAGE(PG8_SB(0, 0), b2, voffB); PG8_STAGE(PG8_SB(0, 1), b2 + hstepB, voffB); PG8_STAGE(PG8_SA(0, 0), a2, voffA);
;             PG8_WAIT_V(8); PG8_WAIT_L(0); PG8_BAR; PG8_MMA(1, 0, At, B0); PG8_MMA(1, 1, At, B1); PG8_BAR; PG8_SCHED;
.LBB0_745:
	ds_read_b128 v[150:153], v147
	ds_read_b128 v[154:157], v147 offset:1024
	ds_read_b128 v[158:161], v147 offset:2048
	ds_read_b128 v[162:165], v147 offset:3072
	ds_read_b128 v[166:169], v148
	ds_read_b128 v[170:173], v148 offset:1024
	ds_read_b128 v[174:177], v148 offset:2048
	ds_read_b128 v[182:185], v148 offset:3072
	s_add_u32 s26, s24, 0x100
	s_addc_u32 s27, s25, 0
	s_cmpk_eq_i32 s66, 0x54
	s_cselect_b32 s31, s5, s27
	s_cselect_b32 s30, s4, s26
	s_cselect_b32 s29, s23, s65
	s_cselect_b32 s28, s22, s64
	v_lshl_add_u64 v[178:179], s[24:25], 0, v[136:137]
	s_add_i32 m0, s36, 0xc000
	ds_read_b128 v[186:189], v149
	ds_read_b128 v[190:193], v149 offset:1024
	ds_read_b128 v[194:197], v149 offset:2048
	ds_read_b128 v[202:205], v149 offset:3072
	ds_read_b128 v[206:209], v149 offset:4096
	ds_read_b128 v[210:213], v149 offset:5120
	ds_read_b128 v[214:217], v149 offset:6144
	ds_read_b128 v[218:221], v149 offset:7168
	global_load_lds_dwordx4 v[178:179], off
	v_lshl_add_u64 v[178:179], s[24:25], 0, v[138:139]
	s_add_i32 m0, s36, 0xe000
	s_nop 0
	global_load_lds_dwordx4 v[178:179], off
	s_waitcnt vmcnt(8)
	s_waitcnt lgkmcnt(0)
	s_setprio 1
	v_mfma_f32_16x16x32_bf16 v[124:127], v[150:153], v[186:189], v[124:127]
	v_mfma_f32_16x16x32_bf16 v[120:123], v[158:161], v[186:189], v[120:123]
	v_mfma_f32_16x16x32_bf16 v[116:119], v[150:153], v[194:197], v[116:119]
	v_mfma_f32_16x16x32_bf16 v[112:115], v[158:161], v[194:197], v[112:115]
	s_barrier
	v_mfma_f32_16x16x32_bf16 v[100:103], v[150:153], v[206:209], v[100:103]
	v_mfma_f32_16x16x32_bf16 v[96:99], v[158:161], v[206:209], v[96:99]
	v_mfma_f32_16x16x32_bf16 v[84:87], v[150:153], v[214:217], v[84:87]
	v_mfma_f32_16x16x32_bf16 v[80:83], v[158:161], v[214:217], v[80:83]
	v_mfma_f32_16x16x32_bf16 v[124:127], v[154:157], v[190:193], v[124:127]
	v_mfma_f32_16x16x32_bf16 v[120:123], v[162:165], v[190:193], v[120:123]
	v_mfma_f32_16x16x32_bf16 v[116:119], v[154:157], v[202:205], v[116:119]
	v_mfma_f32_16x16x32_bf16 v[112:115], v[162:165], v[202:205], v[112:115]
	v_mfma_f32_16x16x32_bf16 v[100:103], v[154:157], v[210:213], v[100:103]
	v_mfma_f32_16x16x32_bf16 v[96:99], v[162:165], v[210:213], v[96:99]
	v_mfma_f32_16x16x32_bf16 v[84:87], v[154:157], v[218:221], v[84:87]
	v_mfma_f32_16x16x32_bf16 v[80:83], v[162:165], v[218:221], v[80:83]
	v_mfma_f32_16x16x32_bf16 v[108:111], v[166:169], v[186:189], v[108:111]
	v_mfma_f32_16x16x32_bf16 v[104:107], v[174:177], v[186:189], v[104:107]
	v_mfma_f32_16x16x32_bf16 v[92:95], v[166:169], v[194:197], v[92:95]
	v_mfma_f32_16x16x32_bf16 v[88:91], v[174:177], v[194:197], v[88:91]
	v_mfma_f32_16x16x32_bf16 v[76:79], v[166:169], v[206:209], v[76:79]
	v_mfma_f32_16x16x32_bf16 v[72:75], v[174:177], v[206:209], v[72:75]
	v_mfma_f32_16x16x32_bf16 v[68:71], v[166:169], v[214:217], v[68:71]
	v_mfma_f32_16x16x32_bf16 v[64:67], v[174:177], v[214:217], v[64:67]
	v_mfma_f32_16x16x32_bf16 v[108:111], v[170:173], v[190:193], v[108:111]
	v_mfma_f32_16x16x32_bf16 v[104:107], v[182:185], v[190:193], v[104:107]
	v_mfma_f32_16x16x32_bf16 v[92:95], v[170:173], v[202:205], v[92:95]
	v_mfma_f32_16x16x32_bf16 v[88:91], v[182:185], v[202:205], v[88:91]
	v_mfma_f32_16x16x32_bf16 v[76:79], v[170:173], v[210:213], v[76:79]
	v_mfma_f32_16x16x32_bf16 v[72:75], v[182:185], v[210:213], v[72:75]
	v_mfma_f32_16x16x32_bf16 v[68:71], v[170:173], v[218:221], v[68:71]
	v_mfma_f32_16x16x32_bf16 v[64:67], v[182:185], v[218:221], v[64:67]
	s_barrier
	s_setprio 0
	s_add_i32 s3, s54, s35
	v_lshl_add_u64 v[178:179], s[28:29], 0, v[130:131]
	s_mov_b32 m0, s3
	ds_read_b128 v[186:189], v149 offset:16384
	ds_read_b128 v[190:193], v149 offset:17408
	ds_read_b128 v[194:197], v149 offset:18432
	ds_read_b128 v[202:205], v149 offset:19456
	ds_read_b128 v[206:209], v149 offset:20480
	ds_read_b128 v[210:213], v149 offset:21504
	ds_read_b128 v[214:217], v149 offset:22528
	ds_read_b128 v[218:221], v149 offset:23552
	global_load_lds_dwordx4 v[178:179], off
	s_add_i32 m0, s3, 0x2000
	s_add_u32 s24, s28, 0x160000
	v_lshl_add_u64 v[198:199], s[28:29], 0, v[134:135]
	s_addc_u32 s25, s29, 0
	s_add_i32 s3, s55, s35
	global_load_lds_dwordx4 v[198:199], off
	v_lshl_add_u64 v[222:223], s[24:25], 0, v[130:131]
	s_mov_b32 m0, s3
	v_lshl_add_u64 v[224:225], s[30:31], 0, v[132:133]
	global_load_lds_dwordx4 v[222:223], off
	v_lshl_add_u64 v[222:223], s[24:25], 0, v[134:135]
	s_add_i32 m0, s3, 0x2000
	s_nop 0
	global_load_lds_dwordx4 v[222:223], off
	v_lshl_add_u64 v[222:223], s[30:31], 0, v[128:129]
	s_mov_b32 m0, s36
	s_nop 0
	global_load_lds_dwordx4 v[222:223], off
	s_mov_b32 m0, s37
	s_nop 0
	global_load_lds_dwordx4 v[224:225], off
	s_waitcnt vmcnt(8)
	s_waitcnt lgkmcnt(0)
	s_setprio 1
	v_mfma_f32_16x16x32_bf16 v[60:63], v[150:153], v[186:189], v[60:63]
	v_mfma_f32_16x16x32_bf16 v[56:59], v[158:161], v[186:189], v[56:59]
	v_mfma_f32_16x16x32_bf16 v[52:55], v[150:153], v[194:197], v[52:55]
	v_mfma_f32_16x16x32_bf16 v[48:51], v[158:161], v[194:197], v[48:51]
	s_barrier
; #define PG8_STAGE(bufoff, gbase, voff) do { _Pragma("unroll") for (int _i = 0; _i < 2; ++_i) \
;         __builtin_amdgcn_global_load_lds((const unsigned*)((const char*)(gbase) + (voff)[_i]), (PG8_LAS unsigned*)(lds + (bufoff) + ldsw + _i * 8192), 16, 0, 0); } while (0)
; #define PG8_LDA(dst, b, h) do { _Pragma("unroll") for (int m = 0; m < 4; ++m) _Pragma("unroll") for (int k = 0; k < 2; ++k) dst[m][k] = *(const PG8_LAS bf16x8*)(lds + PG8_SA(b, h) + aoff + m * 2048 + k * 1024); } while (0)
; #define PG8_LDB(dst, b, h) do { _Pragma("unroll") for (int n = 0; n < 2; ++n) _Pragma("unroll") for (int k = 0; k < 2; ++k) dst[n][k] = *(const PG8_LAS bf16x8*)(lds + PG8_SB(b, h) + boff + n * 2048 + k * 1024); } while (0)
; #define PG8_MMA(ai, bj, At, Bt) do { __builtin_amdgcn_s_setprio(1); _Pragma("unroll") for (int m = 0; m < 4; ++m) _Pragma("unroll") for (int n = 0; n < 2; ++n) _Pragma("unroll") for (int k = 0; k < 2; ++k) \
;         acc[ai][bj][m][n] = __builtin_amdgcn_mfma_f32_16x16x32_bf16(Bt[n][k], At[m][k], acc[ai][bj][m][n], 0, 0, 0); __builtin_amdgcn_s_setprio(0); } while (0)
; #define PG8_WAIT_V(n) asm volatile("s_waitcnt vmcnt(" #n ")" ::: "memory")
; #define PG8_WAIT_L(n) asm volatile("s_waitcnt lgkmcnt(" #n ")" ::: "memory")
; #define PG8_BAR __builtin_amdgcn_s_barrier()
; #define PG8_SCHED __builtin_amdgcn_sched_barrier(0)
; template <class Epi, class Sched, bool ALIGN_EPI = false, bool SP2 = false>
; __device__ __forceinline__ void gemm_phase(PG8_LAS unsigned char* lds, const Gemm g, const Sched& S, const Epi& E) {
;     ...
;             PG8_WAIT_V(8); PG8_WAIT_L(0); PG8_BAR; PG8_MMA(1, 0, At, B0); PG8_MMA(1, 1, At, B1); PG8_BAR; PG8_SCHED;
;             PG8_LDB(B0, 1, 0); PG8_LDB(B1, 1, 1); PG8_SCHED; PG8_LDA(At, 1, 0); PG8_STAGE(PG8_SA(0, 1), a2 + hstepA, voffA);
;             PG8_WAIT_V(8); PG8_WAIT_L(0); PG8_BAR; PG8_MMA(0, 0, At, B0); PG8_MMA(0, 1, At, B1); PG8_BAR; PG8_SCHED;
	v_mfma_f32_16x16x32_bf16 v[36:39], v[150:153], v[206:209], v[36:39]
	v_mfma_f32_16x16x32_bf16 v[32:35], v[158:161], v[206:209], v[32:35]
	v_mfma_f32_16x16x32_bf16 v[20:23], v[150:153], v[214:217], v[20:23]
	v_mfma_f32_16x16x32_bf16 v[16:19], v[158:161], v[214:217], v[16:19]
	v_mfma_f32_16x16x32_bf16 v[60:63], v[154:157], v[190:193], v[60:63]
	v_mfma_f32_16x16x32_bf16 v[56:59], v[162:165], v[190:193], v[56:59]
	v_mfma_f32_16x16x32_bf16 v[52:55], v[154:157], v[202:205], v[52:55]
	v_mfma_f32_16x16x32_bf16 v[48:51], v[162:165], v[202:205], v[48:51]
	v_mfma_f32_16x16x32_bf16 v[36:39], v[154:157], v[210:213], v[36:39]
	v_mfma_f32_16x16x32_bf16 v[32:35], v[162:165], v[210:213], v[32:35]
	v_mfma_f32_16x16x32_bf16 v[20:23], v[154:157], v[218:221], v[20:23]
	v_mfma_f32_16x16x32_bf16 v[16:19], v[162:165], v[218:221], v[16:19]
	v_mfma_f32_16x16x32_bf16 v[44:47], v[166:169], v[186:189], v[44:47]
	v_mfma_f32_16x16x32_bf16 v[40:43], v[174:177], v[186:189], v[40:43]
	v_mfma_f32_16x16x32_bf16 v[28:31], v[166:169], v[194:197], v[28:31]
	v_mfma_f32_16x16x32_bf16 v[24:27], v[174:177], v[194:197], v[24:27]
	v_mfma_f32_16x16x32_bf16 v[12:15], v[166:169], v[206:209], v[12:15]
	v_mfma_f32_16x16x32_bf16 v[8:11], v[174:177], v[206:209], v[8:11]
	v_mfma_f32_16x16x32_bf16 v[4:7], v[166:169], v[214:217], v[4:7]
	v_mfma_f32_16x16x32_bf16 v[0:3], v[174:177], v[214:217], v[0:3]
	v_mfma_f32_16x16x32_bf16 v[44:47], v[170:173], v[190:193], v[44:47]
	v_mfma_f32_16x16x32_bf16 v[40:43], v[182:185], v[190:193], v[40:43]
	v_mfma_f32_16x16x32_bf16 v[28:31], v[170:173], v[202:205], v[28:31]
	v_mfma_f32_16x16x32_bf16 v[24:27], v[182:185], v[202:205], v[24:27]
	v_mfma_f32_16x16x32_bf16 v[12:15], v[170:173], v[210:213], v[12:15]
	v_mfma_f32_16x16x32_bf16 v[8:11], v[182:185], v[210:213], v[8:11]
	v_mfma_f32_16x16x32_bf16 v[4:7], v[170:173], v[218:221], v[4:7]
	v_mfma_f32_16x16x32_bf16 v[0:3], v[182:185], v[218:221], v[0:3]
	s_barrier
	s_setprio 0
	s_add_i32 s3, 0, 0x18000
	s_add_i32 s44, 0, 0x1c000
	v_add_u32_e32 v162, s3, v145
	v_add_u32_e32 v182, s44, v145
	ds_read_b128 v[150:153], v162
	ds_read_b128 v[154:157], v162 offset:1024
	ds_read_b128 v[158:161], v162 offset:2048
	ds_read_b128 v[162:165], v162 offset:3072
	ds_read_b128 v[166:169], v182
	ds_read_b128 v[170:173], v182 offset:1024
	ds_read_b128 v[174:177], v182 offset:2048
	ds_read_b128 v[182:185], v182 offset:3072
	s_add_u32 s24, s30, 0x160000
	s_addc_u32 s25, s31, 0
	s_mov_b32 m0, s38
	v_lshl_add_u64 v[226:227], s[24:25], 0, v[128:129]
	ds_read_b128 v[186:189], v149 offset:32768
	ds_read_b128 v[190:193], v149 offset:33792
	ds_read_b128 v[194:197], v149 offset:34816
	ds_read_b128 v[202:205], v149 offset:35840
	ds_read_b128 v[206:209], v149 offset:36864
	ds_read_b128 v[210:213], v149 offset:37888
	ds_read_b128 v[214:217], v149 offset:38912
	ds_read_b128 v[218:221], v149 offset:39936
	global_load_lds_dwordx4 v[226:227], off
	v_lshl_add_u64 v[226:227], s[24:25], 0, v[132:133]
	s_mov_b32 m0, s39
	s_nop 0
	global_load_lds_dwordx4 v[226:227], off
	s_waitcnt vmcnt(8)
	s_waitcnt lgkmcnt(0)
	s_setprio 1
	v_mfma_f32_16x16x32_bf16 v[124:127], v[150:153], v[186:189], v[124:127]
	v_mfma_f32_16x16x32_bf16 v[120:123], v[158:161], v[186:189], v[120:123]
	v_mfma_f32_16x16x32_bf16 v[116:119], v[150:153], v[194:197], v[116:119]
	v_mfma_f32_16x16x32_bf16 v[112:115], v[158:161], v[194:197], v[112:115]
	s_barrier
	v_mfma_f32_16x16x32_bf16 v[100:103], v[150:153], v[206:209], v[100:103]
	v_mfma_f32_16x16x32_bf16 v[96:99], v[158:161], v[206:209], v[96:99]
	v_mfma_f32_16x16x32_bf16 v[84:87], v[150:153], v[214:217], v[84:87]
	v_mfma_f32_16x16x32_bf16 v[80:83], v[158:161], v[214:217], v[80:83]
	v_mfma_f32_16x16x32_bf16 v[124:127], v[154:157], v[190:193], v[124:127]
	v_mfma_f32_16x16x32_bf16 v[120:123], v[162:165], v[190:193], v[120:123]
	v_mfma_f32_16x16x32_bf16 v[116:119], v[154:157], v[202:205], v[116:119]
	v_mfma_f32_16x16x32_bf16 v[112:115], v[162:165], v[202:205], v[112:115]
	v_mfma_f32_16x16x32_bf16 v[100:103], v[154:157], v[210:213], v[100:103]
	v_mfma_f32_16x16x32_bf16 v[96:99], v[162:165], v[210:213], v[96:99]
	v_mfma_f32_16x16x32_bf16 v[84:87], v[154:157], v[218:221], v[84:87]
	v_mfma_f32_16x16x32_bf16 v[80:83], v[162:165], v[218:221], v[80:83]
	v_mfma_f32_16x16x32_bf16 v[108:111], v[166:169], v[186:189], v[108:111]
	v_mfma_f32_16x16x32_bf16 v[104:107], v[174:177], v[186:189], v[104:107]
	v_mfma_f32_16x16x32_bf16 v[92:95], v[166:169], v[194:197], v[92:95]
	v_mfma_f32_16x16x32_bf16 v[88:91], v[174:177], v[194:197], v[88:91]
	v_mfma_f32_16x16x32_bf16 v[76:79], v[166:169], v[206:209], v[76:79]
	v_mfma_f32_16x16x32_bf16 v[72:75], v[174:177], v[206:209], v[72:75]
	v_mfma_f32_16x16x32_bf16 v[68:71], v[166:169], v[214:217], v[68:71]
	v_mfma_f32_16x16x32_bf16 v[64:67], v[174:177], v[214:217], v[64:67]
	v_mfma_f32_16x16x32_bf16 v[108:111], v[170:173], v[190:193], v[108:111]
	v_mfma_f32_16x16x32_bf16 v[104:107], v[182:185], v[190:193], v[104:107]
	v_mfma_f32_16x16x32_bf16 v[92:95], v[170:173], v[202:205], v[92:95]
	v_mfma_f32_16x16x32_bf16 v[88:91], v[182:185], v[202:205], v[88:91]
	v_mfma_f32_16x16x32_bf16 v[76:79], v[170:173], v[210:213], v[76:79]
	v_mfma_f32_16x16x32_bf16 v[72:75], v[182:185], v[210:213], v[72:75]
	v_mfma_f32_16x16x32_bf16 v[68:71], v[170:173], v[218:221], v[68:71]
	v_mfma_f32_16x16x32_bf16 v[64:67], v[182:185], v[218:221], v[64:67]
	s_barrier
; #define PG8_STAGE(bufoff, gbase, voff) do { _Pragma("unroll") for (int _i = 0; _i < 2; ++_i) \
;         __builtin_amdgcn_global_load_lds((const unsigned*)((const char*)(gbase) + (voff)[_i]), (PG8_LAS unsigned*)(lds + (bufoff) + ldsw + _i * 8192), 16, 0, 0); } while (0)
; #define PG8_LDA(dst, b, h) do { _Pragma("unroll") for (int m = 0; m < 4; ++m) _Pragma("unroll") for (int k = 0; k < 2; ++k) dst[m][k] = *(const PG8_LAS bf16x8*)(lds + PG8_SA(b, h) + aoff + m * 2048 + k * 1024); } while (0)
; #define PG8_MMA(ai, bj, At, Bt) do { __builtin_amdgcn_s_setprio(1); _Pragma("unroll") for (int m = 0; m < 4; ++m) _Pragma("unroll") for (int n = 0; n < 2; ++n) _Pragma("unroll") for (int k = 0; k < 2; ++k) \
;         acc[ai][bj][m][n] = __builtin_amdgcn_mfma_f32_16x16x32_bf16(Bt[n][k], At[m][k], acc[ai][bj][m][n], 0, 0, 0); __builtin_amdgcn_s_setprio(0); } while (0)
; #define PG8_WAIT_V(n) asm volatile("s_waitcnt vmcnt(" #n ")" ::: "memory")
; #define PG8_WAIT_L(n) asm volatile("s_waitcnt lgkmcnt(" #n ")" ::: "memory")
; #define PG8_BAR __builtin_amdgcn_s_barrier()
; #define PG8_SCHED __builtin_amdgcn_sched_barrier(0)
; template <class Epi, class Sched, bool ALIGN_EPI = false, bool SP2 = false>
; __device__ __forceinline__ void gemm_phase(PG8_LAS unsigned char* lds, const Gemm g, const Sched& S, const Epi& E) {
;     ...
;             PG8_WAIT_V(8); PG8_WAIT_L(0); PG8_BAR; PG8_MMA(0, 0, At, B0); PG8_MMA(0, 1, At, B1); PG8_BAR; PG8_SCHED;
;             PG8_LDA(At, 1, 1); PG8_STAGE(PG8_SB(1, 0), b3, voffB); PG8_STAGE(PG8_SB(1, 1), b3 + hstepB, voffB); PG8_STAGE(PG8_SA(1, 0), a3, voffA);
;             PG8_WAIT_V(8); PG8_WAIT_L(0); PG8_BAR; PG8_MMA(1, 0, At, B0); PG8_MMA(1, 1, At, B1); PG8_BAR; PG8_SCHED;
;     ...
;         if constexpr (ALIGN_EPI) { if (wr == 0) PG8_BAR; }
	s_setprio 0
	s_add_i32 s3, s3, s35
	v_lshl_add_u64 v[178:179], v[178:179], 0, s[10:11]
	s_mov_b32 m0, s3
	ds_read_b128 v[186:189], v149 offset:49152
	ds_read_b128 v[190:193], v149 offset:50176
	ds_read_b128 v[194:197], v149 offset:51200
	ds_read_b128 v[202:205], v149 offset:52224
	ds_read_b128 v[206:209], v149 offset:53248
	ds_read_b128 v[210:213], v149 offset:54272
	ds_read_b128 v[214:217], v149 offset:55296
	ds_read_b128 v[218:221], v149 offset:56320
	global_load_lds_dwordx4 v[178:179], off
	s_add_i32 m0, s3, 0x2000
	s_add_u32 s24, s28, 0x160080
	v_lshl_add_u64 v[178:179], v[198:199], 0, s[10:11]
	s_addc_u32 s25, s29, 0
	s_add_i32 s3, s44, s35
	global_load_lds_dwordx4 v[178:179], off
	v_lshl_add_u64 v[178:179], s[24:25], 0, v[130:131]
	s_mov_b32 m0, s3
	s_nop 0
	global_load_lds_dwordx4 v[178:179], off
	v_lshl_add_u64 v[178:179], s[24:25], 0, v[134:135]
	s_add_i32 m0, s3, 0x2000
	s_nop 0
	global_load_lds_dwordx4 v[178:179], off
	v_lshl_add_u64 v[178:179], v[222:223], 0, s[10:11]
	s_mov_b32 m0, s50
	s_nop 0
	global_load_lds_dwordx4 v[178:179], off
	v_lshl_add_u64 v[178:179], v[224:225], 0, s[10:11]
	s_mov_b32 m0, s51
	s_nop 0
	global_load_lds_dwordx4 v[178:179], off
	s_waitcnt vmcnt(8)
	s_waitcnt lgkmcnt(0)
	s_setprio 1
	v_mfma_f32_16x16x32_bf16 v[60:63], v[150:153], v[186:189], v[60:63]
	v_mfma_f32_16x16x32_bf16 v[56:59], v[158:161], v[186:189], v[56:59]
	v_mfma_f32_16x16x32_bf16 v[52:55], v[150:153], v[194:197], v[52:55]
	v_mfma_f32_16x16x32_bf16 v[48:51], v[158:161], v[194:197], v[48:51]
	s_barrier
	v_mfma_f32_16x16x32_bf16 v[36:39], v[150:153], v[206:209], v[36:39]
	v_mfma_f32_16x16x32_bf16 v[32:35], v[158:161], v[206:209], v[32:35]
	v_mfma_f32_16x16x32_bf16 v[20:23], v[150:153], v[214:217], v[20:23]
	v_mfma_f32_16x16x32_bf16 v[16:19], v[158:161], v[214:217], v[16:19]
	v_mfma_f32_16x16x32_bf16 v[60:63], v[154:157], v[190:193], v[60:63]
	v_mfma_f32_16x16x32_bf16 v[56:59], v[162:165], v[190:193], v[56:59]
	v_mfma_f32_16x16x32_bf16 v[52:55], v[154:157], v[202:205], v[52:55]
	v_mfma_f32_16x16x32_bf16 v[48:51], v[162:165], v[202:205], v[48:51]
	v_mfma_f32_16x16x32_bf16 v[36:39], v[154:157], v[210:213], v[36:39]
	v_mfma_f32_16x16x32_bf16 v[32:35], v[162:165], v[210:213], v[32:35]
	v_mfma_f32_16x16x32_bf16 v[20:23], v[154:157], v[218:221], v[20:23]
	v_mfma_f32_16x16x32_bf16 v[16:19], v[162:165], v[218:221], v[16:19]
	v_mfma_f32_16x16x32_bf16 v[44:47], v[166:169], v[186:189], v[44:47]
	v_mfma_f32_16x16x32_bf16 v[40:43], v[174:177], v[186:189], v[40:43]
	v_mfma_f32_16x16x32_bf16 v[28:31], v[166:169], v[194:197], v[28:31]
	v_mfma_f32_16x16x32_bf16 v[24:27], v[174:177], v[194:197], v[24:27]
	v_mfma_f32_16x16x32_bf16 v[12:15], v[166:169], v[206:209], v[12:15]
	v_mfma_f32_16x16x32_bf16 v[8:11], v[174:177], v[206:209], v[8:11]
	v_mfma_f32_16x16x32_bf16 v[4:7], v[166:169], v[214:217], v[4:7]
	v_mfma_f32_16x16x32_bf16 v[0:3], v[174:177], v[214:217], v[0:3]
	v_mfma_f32_16x16x32_bf16 v[44:47], v[170:173], v[190:193], v[44:47]
	v_mfma_f32_16x16x32_bf16 v[40:43], v[182:185], v[190:193], v[40:43]
	v_mfma_f32_16x16x32_bf16 v[28:31], v[170:173], v[202:205], v[28:31]
	v_mfma_f32_16x16x32_bf16 v[24:27], v[182:185], v[202:205], v[24:27]
	v_mfma_f32_16x16x32_bf16 v[12:15], v[170:173], v[210:213], v[12:15]
	v_mfma_f32_16x16x32_bf16 v[8:11], v[182:185], v[210:213], v[8:11]
	v_mfma_f32_16x16x32_bf16 v[4:7], v[170:173], v[218:221], v[4:7]
	v_mfma_f32_16x16x32_bf16 v[0:3], v[182:185], v[218:221], v[0:3]
	s_barrier
	s_setprio 0
	s_add_i32 s66, s66, 2
	s_add_u32 s64, s64, 0x100
	s_addc_u32 s65, s65, 0
	s_cmpk_gt_u32 s66, 0x55
	s_mov_b64 s[24:25], s[26:27]
	s_cbranch_scc0 .LBB0_745
	s_and_b64 vcc, exec, s[12:13]
	s_cbranch_vccz .LBB0_748
	s_barrier
